# attention->merged barrier becomes a batch-class barrier; late weights published by write-through stores + a done counter; MKf/MRG overlap kept by a per-class wait
# speedup vs baseline: 1.0377x; 1.0056x over previous
;     float wv[32];
; #pragma unroll
;     for (int i = 0; i < 32; ++i) { const int kk = 2 * i + (lane >> 5); wv[i] = __builtin_nontemporal_load(W + (size_t)(k0 + kk) * ldw + src_c0 + (lane & 31)); }
; #pragma unroll
;     for (int i = 0; i < 32; ++i) { const int kk = 2 * i + (lane >> 5); float w = wv[i] * cscale; if (kgain) w *= kgain[k0 + kk]; scr[kk * 33 + (lane & 31)] = w; }
;     ...
;     for (int it = lo + w; it < NITEMS; it += nw) {
;         int r = it;
;         if (r < I_BR) { const int kb = r / 32, gi = r % 32; tr_item(F.w_bsb, D, DH, F.Wbr_t, 32 * gi, 32 * gi, 64 * kb, scr, F.lane); continue; } r -= I_BR;
;         if (r < I_BR) { const int kb = r / 32, gi = r % 32; tr_item(F.w_bfx, D, DH, F.Wbr_t + (size_t)D * DH, 32 * gi, 32 * gi, 64 * kb, scr, F.lane); continue; } r -= I_BR;
;         if (r < I_BR) { const int kb = r / 32, gi = r % 32; tr_item(F.w_bmm, D, DH, F.Wbr_t + (size_t)2 * D * DH, 32 * gi, 32 * gi, 64 * kb, scr, F.lane); continue; } r -= I_BR;
;         if (r < I_OUT) { const int kb = r / 32, gi = r % 32; tr_item(F.w_out, D, D, F.Wout_t, 32 * gi, 32 * gi, 64 * kb, scr, F.lane); continue; } r -= I_OUT;
;         if (r < I_UP) { const int kb = r / 128, gi = r % 128; tr_item(F.w_up, FF, D, F.Wup_t, 32 * gi, 32 * gi, 64 * kb, scr, F.lane, F.g_mlp); continue; } r -= I_UP;
;         { const int kb = r / 32, gi = r % 32; tr_item(F.w_dn, D, FF, F.Wdn_t, 32 * gi, 32 * gi, 64 * kb, scr, F.lane); }
.LBB0_269:
	s_cmpk_gt_i32 s22, 0xff
	s_mov_b64 s[2:3], -1
	s_cbranch_scc0 .LBB0_311
	s_cmpk_gt_u32 s22, 0x1ff
	s_cbranch_scc0 .LBB0_308
	s_cmpk_gt_u32 s22, 0x2ff
	s_cbranch_scc0 .LBB0_305
	s_cmpk_gt_u32 s22, 0x4ff
	s_cbranch_scc0 .LBB0_302
	s_cmpk_gt_u32 s22, 0xcff
	s_cbranch_scc0 .LBB0_275
	s_and_b32 s2, s15, 0x7fffffc0
	s_addk_i32 s2, 0xe600
	s_and_b32 s4, s14, 0x3e0
	v_or_b32_e32 v2, s2, v48
	s_lshl_b32 s8, s4, 2
	v_or_b32_e32 v32, 2, v2
	v_mov_b32_e32 v33, v3
	v_or_b32_e32 v34, 4, v2
	v_mov_b32_e32 v35, v3
	v_or_b32_e32 v36, 6, v2
	v_mov_b32_e32 v37, v3
	v_or_b32_e32 v38, 8, v2
	v_mov_b32_e32 v39, v3
	v_or_b32_e32 v40, 10, v2
	v_mov_b32_e32 v41, v3
	v_or_b32_e32 v42, 12, v2
	v_mov_b32_e32 v43, v3
	v_lshl_add_u64 v[28:29], v[4:5], 0, s[8:9]
	v_lshlrev_b64 v[30:31], 12, v[2:3]
	v_lshlrev_b64 v[32:33], 12, v[32:33]
	v_lshlrev_b64 v[34:35], 12, v[34:35]
	v_lshlrev_b64 v[36:37], 12, v[36:37]
	v_lshlrev_b64 v[38:39], 12, v[38:39]
	v_lshlrev_b64 v[40:41], 12, v[40:41]
	v_lshlrev_b64 v[42:43], 12, v[42:43]
	v_or_b32_e32 v44, 14, v2
	v_mov_b32_e32 v45, v3
	v_lshl_add_u64 v[30:31], v[28:29], 0, v[30:31]
	v_lshl_add_u64 v[32:33], v[28:29], 0, v[32:33]
	v_lshl_add_u64 v[34:35], v[28:29], 0, v[34:35]
	v_lshl_add_u64 v[36:37], v[28:29], 0, v[36:37]
	v_lshl_add_u64 v[38:39], v[28:29], 0, v[38:39]
	v_lshl_add_u64 v[40:41], v[28:29], 0, v[40:41]
	v_lshl_add_u64 v[42:43], v[28:29], 0, v[42:43]
	v_lshlrev_b64 v[44:45], 12, v[44:45]
	v_lshl_add_u64 v[44:45], v[28:29], 0, v[44:45]
	global_load_dword v46, v[30:31], off nt
	global_load_dword v47, v[32:33], off nt
	global_load_dword v68, v[34:35], off nt
	global_load_dword v69, v[36:37], off nt
	global_load_dword v70, v[38:39], off nt
	global_load_dword v71, v[40:41], off nt
	global_load_dword v72, v[42:43], off nt
	global_load_dword v73, v[44:45], off nt
	v_or_b32_e32 v30, 16, v2
	v_mov_b32_e32 v31, v3
	v_or_b32_e32 v32, 18, v2
	v_mov_b32_e32 v33, v3
	v_or_b32_e32 v34, 20, v2
	v_mov_b32_e32 v35, v3
	v_or_b32_e32 v36, 22, v2
	v_mov_b32_e32 v37, v3
	v_or_b32_e32 v38, 24, v2
	v_mov_b32_e32 v39, v3
	v_or_b32_e32 v40, 26, v2
	v_mov_b32_e32 v41, v3
	v_or_b32_e32 v42, 28, v2
	v_mov_b32_e32 v43, v3
	v_lshlrev_b64 v[30:31], 12, v[30:31]
	v_lshlrev_b64 v[32:33], 12, v[32:33]
	v_lshlrev_b64 v[34:35], 12, v[34:35]
	v_lshlrev_b64 v[36:37], 12, v[36:37]
	v_lshlrev_b64 v[38:39], 12, v[38:39]
	v_lshlrev_b64 v[40:41], 12, v[40:41]
	v_lshlrev_b64 v[42:43], 12, v[42:43]
	v_or_b32_e32 v44, 30, v2
	v_mov_b32_e32 v45, v3
	v_lshl_add_u64 v[30:31], v[28:29], 0, v[30:31]
	v_lshl_add_u64 v[32:33], v[28:29], 0, v[32:33]
	v_lshl_add_u64 v[34:35], v[28:29], 0, v[34:35]
	v_lshl_add_u64 v[36:37], v[28:29], 0, v[36:37]
	v_lshl_add_u64 v[38:39], v[28:29], 0, v[38:39]
	v_lshl_add_u64 v[40:41], v[28:29], 0, v[40:41]
	v_lshl_add_u64 v[42:43], v[28:29], 0, v[42:43]
	v_lshlrev_b64 v[44:45], 12, v[44:45]
	v_lshl_add_u64 v[44:45], v[28:29], 0, v[44:45]
	global_load_dword v74, v[30:31], off nt
	global_load_dword v75, v[32:33], off nt
	global_load_dword v76, v[34:35], off nt
	global_load_dword v77, v[36:37], off nt
	global_load_dword v78, v[38:39], off nt
	global_load_dword v79, v[40:41], off nt
	global_load_dword v80, v[42:43], off nt
	global_load_dword v81, v[44:45], off nt
	v_or_b32_e32 v30, 32, v2
	v_mov_b32_e32 v31, v3
	v_or_b32_e32 v32, 34, v2
	v_mov_b32_e32 v33, v3
	v_or_b32_e32 v34, 36, v2
	v_mov_b32_e32 v35, v3
	v_or_b32_e32 v36, 38, v2
	v_mov_b32_e32 v37, v3
	v_or_b32_e32 v38, 40, v2
	v_mov_b32_e32 v39, v3
	v_or_b32_e32 v40, 42, v2
	v_mov_b32_e32 v41, v3
	v_or_b32_e32 v42, 44, v2
	v_mov_b32_e32 v43, v3
	v_lshlrev_b64 v[30:31], 12, v[30:31]
	v_lshlrev_b64 v[32:33], 12, v[32:33]
	v_lshlrev_b64 v[34:35], 12, v[34:35]
	v_lshlrev_b64 v[36:37], 12, v[36:37]
	v_lshlrev_b64 v[38:39], 12, v[38:39]
	v_lshlrev_b64 v[40:41], 12, v[40:41]
	v_lshlrev_b64 v[42:43], 12, v[42:43]
	v_or_b32_e32 v44, 46, v2
	v_mov_b32_e32 v45, v3
	v_lshl_add_u64 v[30:31], v[28:29], 0, v[30:31]
	v_lshl_add_u64 v[32:33], v[28:29], 0, v[32:33]
	v_lshl_add_u64 v[34:35], v[28:29], 0, v[34:35]
	v_lshl_add_u64 v[36:37], v[28:29], 0, v[36:37]
	v_lshl_add_u64 v[38:39], v[28:29], 0, v[38:39]
	v_lshl_add_u64 v[40:41], v[28:29], 0, v[40:41]
	v_lshl_add_u64 v[42:43], v[28:29], 0, v[42:43]
	v_lshlrev_b64 v[44:45], 12, v[44:45]
	v_lshl_add_u64 v[44:45], v[28:29], 0, v[44:45]
	global_load_dword v82, v[30:31], off nt
	global_load_dword v83, v[32:33], off nt
	global_load_dword v84, v[34:35], off nt
	global_load_dword v85, v[36:37], off nt
	global_load_dword v86, v[38:39], off nt
	global_load_dword v87, v[40:41], off nt
	global_load_dword v88, v[42:43], off nt
	global_load_dword v89, v[44:45], off nt
	v_or_b32_e32 v30, 48, v2
	v_mov_b32_e32 v31, v3
	v_or_b32_e32 v32, 50, v2
	v_mov_b32_e32 v33, v3
	v_or_b32_e32 v34, 52, v2
	v_mov_b32_e32 v35, v3
	v_or_b32_e32 v36, 54, v2
	v_mov_b32_e32 v37, v3
	v_or_b32_e32 v38, 56, v2
	v_mov_b32_e32 v39, v3
	v_or_b32_e32 v40, 58, v2
	v_mov_b32_e32 v41, v3
	v_or_b32_e32 v42, 60, v2
	v_mov_b32_e32 v43, v3
	v_or_b32_e32 v2, 62, v2
	v_lshlrev_b64 v[30:31], 12, v[30:31]
	v_lshlrev_b64 v[32:33], 12, v[32:33]
	v_lshlrev_b64 v[34:35], 12, v[34:35]
	v_lshlrev_b64 v[36:37], 12, v[36:37]
	v_lshlrev_b64 v[38:39], 12, v[38:39]
	v_lshlrev_b64 v[40:41], 12, v[40:41]
	v_lshlrev_b64 v[42:43], 12, v[42:43]
	v_lshlrev_b64 v[44:45], 12, v[2:3]
	v_lshl_add_u64 v[30:31], v[28:29], 0, v[30:31]
	v_lshl_add_u64 v[32:33], v[28:29], 0, v[32:33]
	v_lshl_add_u64 v[34:35], v[28:29], 0, v[34:35]
	v_lshl_add_u64 v[36:37], v[28:29], 0, v[36:37]
	v_lshl_add_u64 v[38:39], v[28:29], 0, v[38:39]
	v_lshl_add_u64 v[40:41], v[28:29], 0, v[40:41]
	v_lshl_add_u64 v[42:43], v[28:29], 0, v[42:43]
	v_lshl_add_u64 v[28:29], v[28:29], 0, v[44:45]
	global_load_dword v2, v[30:31], off nt
	s_nop 0
	global_load_dword v30, v[32:33], off nt
	global_load_dword v31, v[34:35], off nt
	s_nop 0
	global_load_dword v32, v[36:37], off nt
	global_load_dword v33, v[38:39], off nt
	global_load_dword v34, v[40:41], off nt
	global_load_dword v35, v[42:43], off nt
	s_nop 0
	global_load_dword v28, v[28:29], off nt
	s_waitcnt vmcnt(30)
; #define GAS __attribute__((address_space(1)))
; #define LAS __attribute__((address_space(3)))
; #define LDS_WAIT() asm volatile("s_waitcnt lgkmcnt(0)" ::: "memory")
; __device__ __forceinline__ unsigned pk2(float lo, float hi) { return f2bf(lo) | (f2bf(hi) << 16); }
;     ...
;     for (int i = 0; i < 32; ++i) { const int kk = 2 * i + (lane >> 5); float w = wv[i] * cscale; if (kgain) w *= kgain[k0 + kk]; scr[kk * 33 + (lane & 31)] = w; }
;     LDS_WAIT(); asm volatile("" ::: "memory");
;     const int c = lane & 7;
; #pragma unroll
;     for (int j = 0; j < 4; ++j) { const int n = (lane >> 3) + 8 * j; const LAS float* s = scr + (8 * c) * 33 + n;
;         v4u o; o.x = pk2(s[0 * 33], s[1 * 33]); o.y = pk2(s[2 * 33], s[3 * 33]); o.z = pk2(s[4 * 33], s[5 * 33]); o.w = pk2(s[6 * 33], s[7 * 33]);
;         *(GAS v4u*)(WT + (size_t)(dst_r0 + n) * K + k0 + 8 * c) = o; }
;     LDS_WAIT(); asm volatile("" ::: "memory");
	ds_write2_b32 v49, v46, v47 offset1:66
	s_waitcnt vmcnt(28)
	ds_write2_b32 v49, v68, v69 offset0:132 offset1:198
	s_waitcnt vmcnt(26)
	ds_write2_b32 v58, v70, v71 offset0:8 offset1:74
	s_waitcnt vmcnt(24)
	ds_write2_b32 v58, v72, v73 offset0:140 offset1:206
	s_waitcnt vmcnt(22)
	ds_write2_b32 v59, v74, v75 offset0:16 offset1:82
	s_waitcnt vmcnt(20)
	ds_write2_b32 v59, v76, v77 offset0:148 offset1:214
	s_waitcnt vmcnt(18)
	ds_write2_b32 v60, v78, v79 offset0:24 offset1:90
	s_waitcnt vmcnt(16)
	ds_write2_b32 v60, v80, v81 offset0:156 offset1:222
	s_waitcnt vmcnt(14)
	ds_write2_b32 v61, v82, v83 offset0:32 offset1:98
	s_waitcnt vmcnt(12)
	ds_write2_b32 v61, v84, v85 offset0:164 offset1:230
	s_waitcnt vmcnt(10)
	ds_write2_b32 v62, v86, v87 offset0:40 offset1:106
	s_waitcnt vmcnt(8)
	ds_write2_b32 v62, v88, v89 offset0:172 offset1:238
	s_waitcnt vmcnt(6)
	ds_write2_b32 v63, v2, v30 offset0:48 offset1:114
	s_waitcnt vmcnt(4)
	ds_write2_b32 v63, v31, v32 offset0:180 offset1:246
	s_waitcnt vmcnt(2)
	ds_write2_b32 v64, v33, v34 offset0:56 offset1:122
	s_waitcnt vmcnt(0)
	ds_write2_b32 v64, v35, v28 offset0:188 offset1:254
	s_waitcnt lgkmcnt(0)
	ds_read2_b32 v[32:33], v51 offset1:8
	ds_read2_b32 v[36:37], v51 offset0:33 offset1:41
	ds_read2_b32 v[38:39], v51 offset0:66 offset1:74
	ds_read2_b32 v[40:41], v51 offset0:99 offset1:107
	ds_read2_b32 v[42:43], v51 offset0:132 offset1:140
	s_waitcnt lgkmcnt(4)
	v_bfe_u32 v2, v32, 16, 1
	v_add3_u32 v2, v32, v2, s19
	s_waitcnt lgkmcnt(3)
	v_bfe_u32 v28, v36, 16, 1
	v_lshrrev_b32_e32 v2, 16, v2
	v_add3_u32 v28, v36, v28, s19
	ds_read2_b32 v[44:45], v51 offset0:165 offset1:173
	v_and_or_b32 v28, v28, s20, v2
	s_waitcnt lgkmcnt(3)
	v_bfe_u32 v2, v38, 16, 1
	v_add3_u32 v2, v38, v2, s19
	s_waitcnt lgkmcnt(2)
	v_bfe_u32 v29, v40, 16, 1
	ds_read2_b32 v[46:47], v51 offset0:198 offset1:206
	v_lshrrev_b32_e32 v2, 16, v2
	v_add3_u32 v29, v40, v29, s19
	ds_read2_b32 v[68:69], v51 offset0:231 offset1:239
	v_and_or_b32 v29, v29, s20, v2
	s_waitcnt lgkmcnt(3)
	v_bfe_u32 v2, v42, 16, 1
	v_add3_u32 v2, v42, v2, s19
	s_waitcnt lgkmcnt(2)
	v_bfe_u32 v30, v44, 16, 1
	v_lshrrev_b32_e32 v2, 16, v2
	v_add3_u32 v30, v44, v30, s19
	v_and_or_b32 v30, v30, s20, v2
	s_waitcnt lgkmcnt(1)
	v_bfe_u32 v2, v46, 16, 1
	v_add3_u32 v2, v46, v2, s19
	s_waitcnt lgkmcnt(0)
	v_bfe_u32 v31, v68, 16, 1
	v_lshrrev_b32_e32 v2, 16, v2
	v_add3_u32 v31, v68, v31, s19
	s_mov_b32 s3, s9
	v_and_or_b32 v31, v31, s20, v2
	v_or_b32_e32 v2, s4, v50
	v_lshl_add_u64 v[34:35], s[2:3], 1, v[6:7]
	v_lshlrev_b32_e32 v2, 13, v2
	v_lshl_add_u64 v[70:71], v[34:35], 0, v[2:3]
	v_bfe_u32 v2, v33, 16, 1
	global_store_dwordx4 v[70:71], v[28:31], off sc1
	v_add3_u32 v2, v33, v2, s19
	v_lshrrev_b32_e32 v2, 16, v2
	v_bfe_u32 v28, v37, 16, 1
	v_add3_u32 v28, v37, v28, s19
	v_and_or_b32 v28, v28, s20, v2
	v_bfe_u32 v2, v39, 16, 1
	v_add3_u32 v2, v39, v2, s19
	v_bfe_u32 v29, v41, 16, 1
	v_lshrrev_b32_e32 v2, 16, v2
	v_add3_u32 v29, v41, v29, s19
	v_and_or_b32 v29, v29, s20, v2
	v_bfe_u32 v2, v43, 16, 1
	v_add3_u32 v2, v43, v2, s19
	v_bfe_u32 v30, v45, 16, 1
	v_lshrrev_b32_e32 v2, 16, v2
	v_add3_u32 v30, v45, v30, s19
	v_and_or_b32 v30, v30, s20, v2
	v_bfe_u32 v2, v47, 16, 1
	v_add3_u32 v2, v47, v2, s19
	v_bfe_u32 v31, v69, 16, 1
	v_lshrrev_b32_e32 v2, 16, v2
	v_add3_u32 v31, v69, v31, s19
	v_and_or_b32 v31, v31, s20, v2
	v_or_b32_e32 v2, s4, v52
	v_lshlrev_b32_e32 v2, 13, v2
	ds_read2_b32 v[32:33], v51 offset0:16 offset1:24
	v_lshl_add_u64 v[36:37], v[34:35], 0, v[2:3]
	global_store_dwordx4 v[36:37], v[28:31], off sc1
	ds_read2_b32 v[36:37], v51 offset0:49 offset1:57
	ds_read2_b32 v[38:39], v51 offset0:82 offset1:90
	ds_read2_b32 v[40:41], v51 offset0:115 offset1:123
	s_waitcnt lgkmcnt(3)
	v_bfe_u32 v2, v32, 16, 1
	v_add3_u32 v2, v32, v2, s19
	s_waitcnt lgkmcnt(2)
	v_bfe_u32 v28, v36, 16, 1
	ds_read2_b32 v[42:43], v51 offset0:148 offset1:156
	v_lshrrev_b32_e32 v2, 16, v2
	v_add3_u32 v28, v36, v28, s19
	ds_read2_b32 v[44:45], v51 offset0:181 offset1:189
	v_and_or_b32 v28, v28, s20, v2
	s_waitcnt lgkmcnt(3)
	v_bfe_u32 v2, v38, 16, 1
	v_add3_u32 v2, v38, v2, s19
	s_waitcnt lgkmcnt(2)
	v_bfe_u32 v29, v40, 16, 1
	ds_read2_b32 v[46:47], v51 offset0:214 offset1:222
	v_lshrrev_b32_e32 v2, 16, v2
	v_add3_u32 v29, v40, v29, s19
	ds_read2_b32 v[68:69], v51 offset0:247 offset1:255
	v_and_or_b32 v29, v29, s20, v2
	s_waitcnt lgkmcnt(3)
	v_bfe_u32 v2, v42, 16, 1
	v_add3_u32 v2, v42, v2, s19
	s_waitcnt lgkmcnt(2)
	v_bfe_u32 v30, v44, 16, 1
	v_lshrrev_b32_e32 v2, 16, v2
	v_add3_u32 v30, v44, v30, s19
	v_and_or_b32 v30, v30, s20, v2
	s_waitcnt lgkmcnt(1)
	v_bfe_u32 v2, v46, 16, 1
	v_add3_u32 v2, v46, v2, s19
	s_waitcnt lgkmcnt(0)
	v_bfe_u32 v31, v68, 16, 1
	v_lshrrev_b32_e32 v2, 16, v2
	v_add3_u32 v31, v68, v31, s19
	v_and_or_b32 v31, v31, s20, v2
	v_or_b32_e32 v2, s4, v53
	v_lshlrev_b32_e32 v2, 13, v2
	v_lshl_add_u64 v[70:71], v[34:35], 0, v[2:3]
	v_bfe_u32 v2, v33, 16, 1
	global_store_dwordx4 v[70:71], v[28:31], off sc1
	v_add3_u32 v2, v33, v2, s19
	v_lshrrev_b32_e32 v2, 16, v2
	v_bfe_u32 v28, v37, 16, 1
	v_add3_u32 v28, v37, v28, s19
	v_and_or_b32 v28, v28, s20, v2
	v_bfe_u32 v2, v39, 16, 1
	v_add3_u32 v2, v39, v2, s19
	v_bfe_u32 v29, v41, 16, 1
	v_lshrrev_b32_e32 v2, 16, v2
	v_add3_u32 v29, v41, v29, s19
	v_and_or_b32 v29, v29, s20, v2
	v_bfe_u32 v2, v43, 16, 1
	v_add3_u32 v2, v43, v2, s19
	v_bfe_u32 v30, v45, 16, 1
	v_lshrrev_b32_e32 v2, 16, v2
	v_add3_u32 v30, v45, v30, s19
	v_and_or_b32 v30, v30, s20, v2
	v_bfe_u32 v2, v47, 16, 1
	v_add3_u32 v2, v47, v2, s19
	v_bfe_u32 v31, v69, 16, 1
	v_lshrrev_b32_e32 v2, 16, v2
	v_add3_u32 v31, v69, v31, s19
	v_and_or_b32 v31, v31, s20, v2
	v_or_b32_e32 v2, s4, v54
	v_lshlrev_b32_e32 v2, 13, v2
	v_lshl_add_u64 v[32:33], v[34:35], 0, v[2:3]
	global_store_dwordx4 v[32:33], v[28:31], off sc1
	s_waitcnt lgkmcnt(0)
	s_mov_b64 s[2:3], 0

; #define GAS __attribute__((address_space(1)))
; #define LAS __attribute__((address_space(3)))
; #define LDS_WAIT() asm volatile("s_waitcnt lgkmcnt(0)" ::: "memory")
; __device__ __forceinline__ unsigned pk2(float lo, float hi) { return f2bf(lo) | (f2bf(hi) << 16); }
;     ...
;     for (int i = 0; i < 32; ++i) { const int kk = 2 * i + (lane >> 5); float w = wv[i] * cscale; if (kgain) w *= kgain[k0 + kk]; scr[kk * 33 + (lane & 31)] = w; }
;     LDS_WAIT(); asm volatile("" ::: "memory");
;     const int c = lane & 7;
; #pragma unroll
;     for (int j = 0; j < 4; ++j) { const int n = (lane >> 3) + 8 * j; const LAS float* s = scr + (8 * c) * 33 + n;
;         v4u o; o.x = pk2(s[0 * 33], s[1 * 33]); o.y = pk2(s[2 * 33], s[3 * 33]); o.z = pk2(s[4 * 33], s[5 * 33]); o.w = pk2(s[6 * 33], s[7 * 33]);
;         *(GAS v4u*)(WT + (size_t)(dst_r0 + n) * K + k0 + 8 * c) = o; }
;     LDS_WAIT(); asm volatile("" ::: "memory");
.LBB0_300:
	ds_write2_b32 v2, v30, v31 offset0:172 offset1:238
	s_waitcnt lgkmcnt(0)
	s_waitcnt vmcnt(4)
	ds_read2_b32 v[32:33], v51 offset1:8
	ds_read2_b32 v[36:37], v51 offset0:33 offset1:41
	ds_read2_b32 v[38:39], v51 offset0:66 offset1:74
	ds_read2_b32 v[40:41], v51 offset0:99 offset1:107
	ds_read2_b32 v[42:43], v51 offset0:132 offset1:140
	ds_read2_b32 v[44:45], v51 offset0:165 offset1:173
	s_waitcnt lgkmcnt(5)
	v_bfe_u32 v2, v32, 16, 1
	v_add3_u32 v2, v32, v2, s19
	s_waitcnt vmcnt(1) lgkmcnt(4)
	v_bfe_u32 v28, v36, 16, 1
	v_lshrrev_b32_e32 v2, 16, v2
	v_add3_u32 v28, v36, v28, s19
	v_and_or_b32 v28, v28, s20, v2
	s_waitcnt lgkmcnt(3)
	v_bfe_u32 v2, v38, 16, 1
	v_add3_u32 v2, v38, v2, s19
	s_waitcnt vmcnt(0) lgkmcnt(2)
	v_bfe_u32 v29, v40, 16, 1
	ds_read2_b32 v[46:47], v51 offset0:198 offset1:206
	v_lshrrev_b32_e32 v2, 16, v2
	v_add3_u32 v29, v40, v29, s19
	ds_read2_b32 v[68:69], v51 offset0:231 offset1:239
	v_and_or_b32 v29, v29, s20, v2
	s_waitcnt lgkmcnt(3)
	v_bfe_u32 v2, v42, 16, 1
	v_add3_u32 v2, v42, v2, s19
	s_waitcnt lgkmcnt(2)
	v_bfe_u32 v30, v44, 16, 1
	v_lshrrev_b32_e32 v2, 16, v2
	v_add3_u32 v30, v44, v30, s19
	v_and_or_b32 v30, v30, s20, v2
	s_waitcnt lgkmcnt(1)
	v_bfe_u32 v2, v46, 16, 1
	v_add3_u32 v2, v46, v2, s19
	s_waitcnt lgkmcnt(0)
	v_bfe_u32 v31, v68, 16, 1
	v_lshrrev_b32_e32 v2, 16, v2
	v_add3_u32 v31, v68, v31, s19
	s_lshl_b32 s8, s24, 1
	v_and_or_b32 v31, v31, s20, v2
	v_or_b32_e32 v2, s23, v50
	v_lshl_add_u64 v[34:35], v[10:11], 0, s[8:9]
	v_lshlrev_b32_e32 v2, 11, v2
	v_lshl_add_u64 v[70:71], v[34:35], 0, v[2:3]
	v_bfe_u32 v2, v33, 16, 1
	global_store_dwordx4 v[70:71], v[28:31], off sc1
	v_add3_u32 v2, v33, v2, s19
	v_lshrrev_b32_e32 v2, 16, v2
	v_bfe_u32 v28, v37, 16, 1
	v_add3_u32 v28, v37, v28, s19
	v_and_or_b32 v28, v28, s20, v2
	v_bfe_u32 v2, v39, 16, 1
	v_add3_u32 v2, v39, v2, s19
	v_bfe_u32 v29, v41, 16, 1
	v_lshrrev_b32_e32 v2, 16, v2
	v_add3_u32 v29, v41, v29, s19
	v_and_or_b32 v29, v29, s20, v2
	v_bfe_u32 v2, v43, 16, 1
	v_add3_u32 v2, v43, v2, s19
	v_bfe_u32 v30, v45, 16, 1
	v_lshrrev_b32_e32 v2, 16, v2
	v_add3_u32 v30, v45, v30, s19
	v_and_or_b32 v30, v30, s20, v2
	v_bfe_u32 v2, v47, 16, 1
	v_add3_u32 v2, v47, v2, s19
	v_bfe_u32 v31, v69, 16, 1
	v_lshrrev_b32_e32 v2, 16, v2
	v_add3_u32 v31, v69, v31, s19
	v_and_or_b32 v31, v31, s20, v2
	v_or_b32_e32 v2, s23, v52
	v_lshlrev_b32_e32 v2, 11, v2
	ds_read2_b32 v[32:33], v51 offset0:16 offset1:24
	v_lshl_add_u64 v[36:37], v[34:35], 0, v[2:3]
	global_store_dwordx4 v[36:37], v[28:31], off sc1
	ds_read2_b32 v[36:37], v51 offset0:49 offset1:57
	ds_read2_b32 v[38:39], v51 offset0:82 offset1:90
	ds_read2_b32 v[40:41], v51 offset0:115 offset1:123
	s_waitcnt lgkmcnt(3)
	v_bfe_u32 v2, v32, 16, 1
	v_add3_u32 v2, v32, v2, s19
	s_waitcnt lgkmcnt(2)
	v_bfe_u32 v28, v36, 16, 1
	ds_read2_b32 v[42:43], v51 offset0:148 offset1:156
	v_lshrrev_b32_e32 v2, 16, v2
	v_add3_u32 v28, v36, v28, s19
	ds_read2_b32 v[44:45], v51 offset0:181 offset1:189
	v_and_or_b32 v28, v28, s20, v2
	s_waitcnt lgkmcnt(3)
	v_bfe_u32 v2, v38, 16, 1
	v_add3_u32 v2, v38, v2, s19
	s_waitcnt lgkmcnt(2)
	v_bfe_u32 v29, v40, 16, 1
	ds_read2_b32 v[46:47], v51 offset0:214 offset1:222
	v_lshrrev_b32_e32 v2, 16, v2
	v_add3_u32 v29, v40, v29, s19
	ds_read2_b32 v[68:69], v51 offset0:247 offset1:255
	v_and_or_b32 v29, v29, s20, v2
	s_waitcnt lgkmcnt(3)
	v_bfe_u32 v2, v42, 16, 1
	v_add3_u32 v2, v42, v2, s19
	s_waitcnt lgkmcnt(2)
	v_bfe_u32 v30, v44, 16, 1
	v_lshrrev_b32_e32 v2, 16, v2
	v_add3_u32 v30, v44, v30, s19
	v_and_or_b32 v30, v30, s20, v2
	s_waitcnt lgkmcnt(1)
	v_bfe_u32 v2, v46, 16, 1
	v_add3_u32 v2, v46, v2, s19
	s_waitcnt lgkmcnt(0)
	v_bfe_u32 v31, v68, 16, 1
	v_lshrrev_b32_e32 v2, 16, v2
	v_add3_u32 v31, v68, v31, s19
	v_and_or_b32 v31, v31, s20, v2
	v_or_b32_e32 v2, s23, v53
	v_lshlrev_b32_e32 v2, 11, v2
	v_lshl_add_u64 v[70:71], v[34:35], 0, v[2:3]
	v_bfe_u32 v2, v33, 16, 1
	global_store_dwordx4 v[70:71], v[28:31], off sc1
	v_add3_u32 v2, v33, v2, s19
	v_lshrrev_b32_e32 v2, 16, v2
	v_bfe_u32 v28, v37, 16, 1
	v_add3_u32 v28, v37, v28, s19
	v_and_or_b32 v28, v28, s20, v2
	v_bfe_u32 v2, v39, 16, 1
	v_add3_u32 v2, v39, v2, s19
	v_bfe_u32 v29, v41, 16, 1
	v_lshrrev_b32_e32 v2, 16, v2
	v_add3_u32 v29, v41, v29, s19
	v_and_or_b32 v29, v29, s20, v2
	v_bfe_u32 v2, v43, 16, 1
	v_add3_u32 v2, v43, v2, s19
	v_bfe_u32 v30, v45, 16, 1
	v_lshrrev_b32_e32 v2, 16, v2
	v_add3_u32 v30, v45, v30, s19
	v_and_or_b32 v30, v30, s20, v2
	v_bfe_u32 v2, v47, 16, 1
	v_add3_u32 v2, v47, v2, s19
	v_bfe_u32 v31, v69, 16, 1
	v_lshrrev_b32_e32 v2, 16, v2
	v_add3_u32 v31, v69, v31, s19
	v_and_or_b32 v31, v31, s20, v2
	v_or_b32_e32 v2, s23, v54
	v_lshlrev_b32_e32 v2, 11, v2
	v_lshl_add_u64 v[32:33], v[34:35], 0, v[2:3]
	global_store_dwordx4 v[32:33], v[28:31], off sc1
	s_waitcnt lgkmcnt(0)

;     float wv[32];
; #pragma unroll
;     for (int i = 0; i < 32; ++i) { const int kk = 2 * i + (lane >> 5); wv[i] = __builtin_nontemporal_load(W + (size_t)(k0 + kk) * ldw + src_c0 + (lane & 31)); }
; #pragma unroll
;     for (int i = 0; i < 32; ++i) { const int kk = 2 * i + (lane >> 5); float w = wv[i] * cscale; if (kgain) w *= kgain[k0 + kk]; scr[kk * 33 + (lane & 31)] = w; }
;     ...
;         if (r < I_OUT) { const int kb = r / 32, gi = r % 32; tr_item(F.w_out, D, D, F.Wout_t, 32 * gi, 32 * gi, 64 * kb, scr, F.lane); continue; } r -= I_OUT;
.LBB0_302:
	s_andn2_b64 vcc, exec, s[2:3]
	s_cbranch_vccnz .LBB0_304
	s_and_b32 s2, s15, 0xfc0
	s_addk_i32 s2, 0xfa00
	s_and_b32 s4, s14, 0x3e0
	v_or_b32_e32 v2, s2, v48
	s_lshl_b32 s8, s4, 2
	v_or_b32_e32 v32, 2, v2
	v_mov_b32_e32 v33, v3
	v_or_b32_e32 v34, 4, v2
	v_mov_b32_e32 v35, v3
	v_or_b32_e32 v36, 6, v2
	v_mov_b32_e32 v37, v3
	v_or_b32_e32 v38, 8, v2
	v_mov_b32_e32 v39, v3
	v_or_b32_e32 v40, 10, v2
	v_mov_b32_e32 v41, v3
	v_or_b32_e32 v42, 12, v2
	v_mov_b32_e32 v43, v3
	v_lshl_add_u64 v[28:29], v[12:13], 0, s[8:9]
	v_lshlrev_b64 v[30:31], 12, v[2:3]
	v_lshlrev_b64 v[32:33], 12, v[32:33]
	v_lshlrev_b64 v[34:35], 12, v[34:35]
	v_lshlrev_b64 v[36:37], 12, v[36:37]
	v_lshlrev_b64 v[38:39], 12, v[38:39]
	v_lshlrev_b64 v[40:41], 12, v[40:41]
	v_lshlrev_b64 v[42:43], 12, v[42:43]
	v_or_b32_e32 v44, 14, v2
	v_mov_b32_e32 v45, v3
	v_lshl_add_u64 v[30:31], v[28:29], 0, v[30:31]
	v_lshl_add_u64 v[32:33], v[28:29], 0, v[32:33]
	v_lshl_add_u64 v[34:35], v[28:29], 0, v[34:35]
	v_lshl_add_u64 v[36:37], v[28:29], 0, v[36:37]
	v_lshl_add_u64 v[38:39], v[28:29], 0, v[38:39]
	v_lshl_add_u64 v[40:41], v[28:29], 0, v[40:41]
	v_lshl_add_u64 v[42:43], v[28:29], 0, v[42:43]
	v_lshlrev_b64 v[44:45], 12, v[44:45]
	v_lshl_add_u64 v[44:45], v[28:29], 0, v[44:45]
	global_load_dword v46, v[30:31], off nt
	global_load_dword v47, v[32:33], off nt
	global_load_dword v68, v[34:35], off nt
	global_load_dword v69, v[36:37], off nt
	global_load_dword v70, v[38:39], off nt
	global_load_dword v71, v[40:41], off nt
	global_load_dword v72, v[42:43], off nt
	global_load_dword v73, v[44:45], off nt
	v_or_b32_e32 v30, 16, v2
	v_mov_b32_e32 v31, v3
	v_or_b32_e32 v32, 18, v2
	v_mov_b32_e32 v33, v3
	v_or_b32_e32 v34, 20, v2
	v_mov_b32_e32 v35, v3
	v_or_b32_e32 v36, 22, v2
	v_mov_b32_e32 v37, v3
	v_or_b32_e32 v38, 24, v2
	v_mov_b32_e32 v39, v3
	v_or_b32_e32 v40, 26, v2
	v_mov_b32_e32 v41, v3
	v_or_b32_e32 v42, 28, v2
	v_mov_b32_e32 v43, v3
	v_lshlrev_b64 v[30:31], 12, v[30:31]
	v_lshlrev_b64 v[32:33], 12, v[32:33]
	v_lshlrev_b64 v[34:35], 12, v[34:35]
	v_lshlrev_b64 v[36:37], 12, v[36:37]
	v_lshlrev_b64 v[38:39], 12, v[38:39]
	v_lshlrev_b64 v[40:41], 12, v[40:41]
	v_lshlrev_b64 v[42:43], 12, v[42:43]
	v_or_b32_e32 v44, 30, v2
	v_mov_b32_e32 v45, v3
	v_lshl_add_u64 v[30:31], v[28:29], 0, v[30:31]
	v_lshl_add_u64 v[32:33], v[28:29], 0, v[32:33]
	v_lshl_add_u64 v[34:35], v[28:29], 0, v[34:35]
	v_lshl_add_u64 v[36:37], v[28:29], 0, v[36:37]
	v_lshl_add_u64 v[38:39], v[28:29], 0, v[38:39]
	v_lshl_add_u64 v[40:41], v[28:29], 0, v[40:41]
	v_lshl_add_u64 v[42:43], v[28:29], 0, v[42:43]
	v_lshlrev_b64 v[44:45], 12, v[44:45]
	v_lshl_add_u64 v[44:45], v[28:29], 0, v[44:45]
	global_load_dword v74, v[30:31], off nt
	global_load_dword v75, v[32:33], off nt
	global_load_dword v76, v[34:35], off nt
	global_load_dword v77, v[36:37], off nt
	global_load_dword v78, v[38:39], off nt
	global_load_dword v79, v[40:41], off nt
	global_load_dword v80, v[42:43], off nt
	global_load_dword v81, v[44:45], off nt
	v_or_b32_e32 v30, 32, v2
	v_mov_b32_e32 v31, v3
	v_or_b32_e32 v32, 34, v2
	v_mov_b32_e32 v33, v3
	v_or_b32_e32 v34, 36, v2
	v_mov_b32_e32 v35, v3
	v_or_b32_e32 v36, 38, v2
	v_mov_b32_e32 v37, v3
	v_or_b32_e32 v38, 40, v2
	v_mov_b32_e32 v39, v3
	v_or_b32_e32 v40, 42, v2
	v_mov_b32_e32 v41, v3
	v_or_b32_e32 v42, 44, v2
	v_mov_b32_e32 v43, v3
	v_lshlrev_b64 v[30:31], 12, v[30:31]
	v_lshlrev_b64 v[32:33], 12, v[32:33]
	v_lshlrev_b64 v[34:35], 12, v[34:35]
	v_lshlrev_b64 v[36:37], 12, v[36:37]
	v_lshlrev_b64 v[38:39], 12, v[38:39]
	v_lshlrev_b64 v[40:41], 12, v[40:41]
	v_lshlrev_b64 v[42:43], 12, v[42:43]
	v_or_b32_e32 v44, 46, v2
	v_mov_b32_e32 v45, v3
	v_lshl_add_u64 v[30:31], v[28:29], 0, v[30:31]
	v_lshl_add_u64 v[32:33], v[28:29], 0, v[32:33]
	v_lshl_add_u64 v[34:35], v[28:29], 0, v[34:35]
	v_lshl_add_u64 v[36:37], v[28:29], 0, v[36:37]
	v_lshl_add_u64 v[38:39], v[28:29], 0, v[38:39]
	v_lshl_add_u64 v[40:41], v[28:29], 0, v[40:41]
	v_lshl_add_u64 v[42:43], v[28:29], 0, v[42:43]
	v_lshlrev_b64 v[44:45], 12, v[44:45]
	v_lshl_add_u64 v[44:45], v[28:29], 0, v[44:45]
	global_load_dword v82, v[30:31], off nt
	global_load_dword v83, v[32:33], off nt
	global_load_dword v84, v[34:35], off nt
	global_load_dword v85, v[36:37], off nt
	global_load_dword v86, v[38:39], off nt
	global_load_dword v87, v[40:41], off nt
	global_load_dword v88, v[42:43], off nt
	global_load_dword v89, v[44:45], off nt
	v_or_b32_e32 v30, 48, v2
	v_mov_b32_e32 v31, v3
	v_or_b32_e32 v32, 50, v2
	v_mov_b32_e32 v33, v3
	v_or_b32_e32 v34, 52, v2
	v_mov_b32_e32 v35, v3
	v_or_b32_e32 v36, 54, v2
	v_mov_b32_e32 v37, v3
	v_or_b32_e32 v38, 56, v2
	v_mov_b32_e32 v39, v3
	v_or_b32_e32 v40, 58, v2
	v_mov_b32_e32 v41, v3
	v_or_b32_e32 v42, 60, v2
	v_mov_b32_e32 v43, v3
	v_or_b32_e32 v2, 62, v2
	v_lshlrev_b64 v[30:31], 12, v[30:31]
	v_lshlrev_b64 v[32:33], 12, v[32:33]
	v_lshlrev_b64 v[34:35], 12, v[34:35]
	v_lshlrev_b64 v[36:37], 12, v[36:37]
	v_lshlrev_b64 v[38:39], 12, v[38:39]
	v_lshlrev_b64 v[40:41], 12, v[40:41]
	v_lshlrev_b64 v[42:43], 12, v[42:43]
	v_lshlrev_b64 v[44:45], 12, v[2:3]
	v_lshl_add_u64 v[30:31], v[28:29], 0, v[30:31]
	v_lshl_add_u64 v[32:33], v[28:29], 0, v[32:33]
	v_lshl_add_u64 v[34:35], v[28:29], 0, v[34:35]
	v_lshl_add_u64 v[36:37], v[28:29], 0, v[36:37]
	v_lshl_add_u64 v[38:39], v[28:29], 0, v[38:39]
	v_lshl_add_u64 v[40:41], v[28:29], 0, v[40:41]
	v_lshl_add_u64 v[42:43], v[28:29], 0, v[42:43]
	v_lshl_add_u64 v[28:29], v[28:29], 0, v[44:45]
	global_load_dword v2, v[30:31], off nt
	s_nop 0
	global_load_dword v30, v[32:33], off nt
	global_load_dword v31, v[34:35], off nt
	s_nop 0
	global_load_dword v32, v[36:37], off nt
	global_load_dword v33, v[38:39], off nt
	global_load_dword v34, v[40:41], off nt
	global_load_dword v35, v[42:43], off nt
	s_nop 0
	global_load_dword v28, v[28:29], off nt
	s_waitcnt vmcnt(30)
; #define GAS __attribute__((address_space(1)))
; #define LAS __attribute__((address_space(3)))
; #define LDS_WAIT() asm volatile("s_waitcnt lgkmcnt(0)" ::: "memory")
; __device__ __forceinline__ unsigned pk2(float lo, float hi) { return f2bf(lo) | (f2bf(hi) << 16); }
;     ...
;     for (int i = 0; i < 32; ++i) { const int kk = 2 * i + (lane >> 5); float w = wv[i] * cscale; if (kgain) w *= kgain[k0 + kk]; scr[kk * 33 + (lane & 31)] = w; }
;     LDS_WAIT(); asm volatile("" ::: "memory");
;     const int c = lane & 7;
; #pragma unroll
;     for (int j = 0; j < 4; ++j) { const int n = (lane >> 3) + 8 * j; const LAS float* s = scr + (8 * c) * 33 + n;
;         v4u o; o.x = pk2(s[0 * 33], s[1 * 33]); o.y = pk2(s[2 * 33], s[3 * 33]); o.z = pk2(s[4 * 33], s[5 * 33]); o.w = pk2(s[6 * 33], s[7 * 33]);
;         *(GAS v4u*)(WT + (size_t)(dst_r0 + n) * K + k0 + 8 * c) = o; }
;     LDS_WAIT(); asm volatile("" ::: "memory");
	ds_write2_b32 v49, v46, v47 offset1:66
	s_waitcnt vmcnt(28)
	ds_write2_b32 v49, v68, v69 offset0:132 offset1:198
	s_waitcnt vmcnt(26)
	ds_write2_b32 v58, v70, v71 offset0:8 offset1:74
	s_waitcnt vmcnt(24)
	ds_write2_b32 v58, v72, v73 offset0:140 offset1:206
	s_waitcnt vmcnt(22)
	ds_write2_b32 v59, v74, v75 offset0:16 offset1:82
	s_waitcnt vmcnt(20)
	ds_write2_b32 v59, v76, v77 offset0:148 offset1:214
	s_waitcnt vmcnt(18)
	ds_write2_b32 v60, v78, v79 offset0:24 offset1:90
	s_waitcnt vmcnt(16)
	ds_write2_b32 v60, v80, v81 offset0:156 offset1:222
	s_waitcnt vmcnt(14)
	ds_write2_b32 v61, v82, v83 offset0:32 offset1:98
	s_waitcnt vmcnt(12)
	ds_write2_b32 v61, v84, v85 offset0:164 offset1:230
	s_waitcnt vmcnt(10)
	ds_write2_b32 v62, v86, v87 offset0:40 offset1:106
	s_waitcnt vmcnt(8)
	ds_write2_b32 v62, v88, v89 offset0:172 offset1:238
	s_waitcnt vmcnt(6)
	ds_write2_b32 v63, v2, v30 offset0:48 offset1:114
	s_waitcnt vmcnt(4)
	ds_write2_b32 v63, v31, v32 offset0:180 offset1:246
	s_waitcnt vmcnt(2)
	ds_write2_b32 v64, v33, v34 offset0:56 offset1:122
	s_waitcnt vmcnt(0)
	ds_write2_b32 v64, v35, v28 offset0:188 offset1:254
	s_waitcnt lgkmcnt(0)
	ds_read2_b32 v[32:33], v51 offset1:8
	ds_read2_b32 v[36:37], v51 offset0:33 offset1:41
	ds_read2_b32 v[38:39], v51 offset0:66 offset1:74
	ds_read2_b32 v[40:41], v51 offset0:99 offset1:107
	ds_read2_b32 v[42:43], v51 offset0:132 offset1:140
	s_waitcnt lgkmcnt(4)
	v_bfe_u32 v2, v32, 16, 1
	v_add3_u32 v2, v32, v2, s19
	s_waitcnt lgkmcnt(3)
	v_bfe_u32 v28, v36, 16, 1
	v_lshrrev_b32_e32 v2, 16, v2
	v_add3_u32 v28, v36, v28, s19
	ds_read2_b32 v[44:45], v51 offset0:165 offset1:173
	v_and_or_b32 v28, v28, s20, v2
	s_waitcnt lgkmcnt(3)
	v_bfe_u32 v2, v38, 16, 1
	v_add3_u32 v2, v38, v2, s19
	s_waitcnt lgkmcnt(2)
	v_bfe_u32 v29, v40, 16, 1
	ds_read2_b32 v[46:47], v51 offset0:198 offset1:206
	v_lshrrev_b32_e32 v2, 16, v2
	v_add3_u32 v29, v40, v29, s19
	ds_read2_b32 v[68:69], v51 offset0:231 offset1:239
	v_and_or_b32 v29, v29, s20, v2
	s_waitcnt lgkmcnt(3)
	v_bfe_u32 v2, v42, 16, 1
	v_add3_u32 v2, v42, v2, s19
	s_waitcnt lgkmcnt(2)
	v_bfe_u32 v30, v44, 16, 1
	v_lshrrev_b32_e32 v2, 16, v2
	v_add3_u32 v30, v44, v30, s19
	v_and_or_b32 v30, v30, s20, v2
	s_waitcnt lgkmcnt(1)
	v_bfe_u32 v2, v46, 16, 1
	v_add3_u32 v2, v46, v2, s19
	s_waitcnt lgkmcnt(0)
	v_bfe_u32 v31, v68, 16, 1
	v_lshrrev_b32_e32 v2, 16, v2
	v_add3_u32 v31, v68, v31, s19
	s_mov_b32 s3, s9
	v_and_or_b32 v31, v31, s20, v2
	v_or_b32_e32 v2, s4, v50
	v_lshl_add_u64 v[34:35], s[2:3], 1, v[14:15]
	v_lshlrev_b32_e32 v2, 11, v2
	v_lshl_add_u64 v[70:71], v[34:35], 0, v[2:3]
	v_bfe_u32 v2, v33, 16, 1
	global_store_dwordx4 v[70:71], v[28:31], off sc1
	v_add3_u32 v2, v33, v2, s19
	v_lshrrev_b32_e32 v2, 16, v2
	v_bfe_u32 v28, v37, 16, 1
	v_add3_u32 v28, v37, v28, s19
	v_and_or_b32 v28, v28, s20, v2
	v_bfe_u32 v2, v39, 16, 1
	v_add3_u32 v2, v39, v2, s19
	v_bfe_u32 v29, v41, 16, 1
	v_lshrrev_b32_e32 v2, 16, v2
	v_add3_u32 v29, v41, v29, s19
	v_and_or_b32 v29, v29, s20, v2
	v_bfe_u32 v2, v43, 16, 1
	v_add3_u32 v2, v43, v2, s19
	v_bfe_u32 v30, v45, 16, 1
	v_lshrrev_b32_e32 v2, 16, v2
	v_add3_u32 v30, v45, v30, s19
	v_and_or_b32 v30, v30, s20, v2
	v_bfe_u32 v2, v47, 16, 1
	v_add3_u32 v2, v47, v2, s19
	v_bfe_u32 v31, v69, 16, 1
	v_lshrrev_b32_e32 v2, 16, v2
	v_add3_u32 v31, v69, v31, s19
	v_and_or_b32 v31, v31, s20, v2
	v_or_b32_e32 v2, s4, v52
	v_lshlrev_b32_e32 v2, 11, v2
	ds_read2_b32 v[32:33], v51 offset0:16 offset1:24
	v_lshl_add_u64 v[36:37], v[34:35], 0, v[2:3]
	global_store_dwordx4 v[36:37], v[28:31], off sc1
	ds_read2_b32 v[36:37], v51 offset0:49 offset1:57
	ds_read2_b32 v[38:39], v51 offset0:82 offset1:90
	ds_read2_b32 v[40:41], v51 offset0:115 offset1:123
	s_waitcnt lgkmcnt(3)
	v_bfe_u32 v2, v32, 16, 1
	v_add3_u32 v2, v32, v2, s19
	s_waitcnt lgkmcnt(2)
	v_bfe_u32 v28, v36, 16, 1
	ds_read2_b32 v[42:43], v51 offset0:148 offset1:156
	v_lshrrev_b32_e32 v2, 16, v2
	v_add3_u32 v28, v36, v28, s19
	ds_read2_b32 v[44:45], v51 offset0:181 offset1:189
	v_and_or_b32 v28, v28, s20, v2
	s_waitcnt lgkmcnt(3)
	v_bfe_u32 v2, v38, 16, 1
	v_add3_u32 v2, v38, v2, s19
	s_waitcnt lgkmcnt(2)
	v_bfe_u32 v29, v40, 16, 1
	ds_read2_b32 v[46:47], v51 offset0:214 offset1:222
	v_lshrrev_b32_e32 v2, 16, v2
	v_add3_u32 v29, v40, v29, s19
	ds_read2_b32 v[68:69], v51 offset0:247 offset1:255
	v_and_or_b32 v29, v29, s20, v2
	s_waitcnt lgkmcnt(3)
	v_bfe_u32 v2, v42, 16, 1
	v_add3_u32 v2, v42, v2, s19
	s_waitcnt lgkmcnt(2)
	v_bfe_u32 v30, v44, 16, 1
	v_lshrrev_b32_e32 v2, 16, v2
	v_add3_u32 v30, v44, v30, s19
	v_and_or_b32 v30, v30, s20, v2
	s_waitcnt lgkmcnt(1)
	v_bfe_u32 v2, v46, 16, 1
	v_add3_u32 v2, v46, v2, s19
	s_waitcnt lgkmcnt(0)
	v_bfe_u32 v31, v68, 16, 1
	v_lshrrev_b32_e32 v2, 16, v2
	v_add3_u32 v31, v68, v31, s19
	v_and_or_b32 v31, v31, s20, v2
	v_or_b32_e32 v2, s4, v53
	v_lshlrev_b32_e32 v2, 11, v2
	v_lshl_add_u64 v[70:71], v[34:35], 0, v[2:3]
	v_bfe_u32 v2, v33, 16, 1
	global_store_dwordx4 v[70:71], v[28:31], off sc1
	v_add3_u32 v2, v33, v2, s19
	v_lshrrev_b32_e32 v2, 16, v2
	v_bfe_u32 v28, v37, 16, 1
	v_add3_u32 v28, v37, v28, s19
	v_and_or_b32 v28, v28, s20, v2
	v_bfe_u32 v2, v39, 16, 1
	v_add3_u32 v2, v39, v2, s19
	v_bfe_u32 v29, v41, 16, 1
	v_lshrrev_b32_e32 v2, 16, v2
	v_add3_u32 v29, v41, v29, s19
	v_and_or_b32 v29, v29, s20, v2
	v_bfe_u32 v2, v43, 16, 1
	v_add3_u32 v2, v43, v2, s19
	v_bfe_u32 v30, v45, 16, 1
	v_lshrrev_b32_e32 v2, 16, v2
	v_add3_u32 v30, v45, v30, s19
	v_and_or_b32 v30, v30, s20, v2
	v_bfe_u32 v2, v47, 16, 1
	v_add3_u32 v2, v47, v2, s19
	v_bfe_u32 v31, v69, 16, 1
	v_lshrrev_b32_e32 v2, 16, v2
	v_add3_u32 v31, v69, v31, s19
	v_and_or_b32 v31, v31, s20, v2
	v_or_b32_e32 v2, s4, v54
	v_lshlrev_b32_e32 v2, 11, v2
	v_lshl_add_u64 v[32:33], v[34:35], 0, v[2:3]
	global_store_dwordx4 v[32:33], v[28:31], off sc1
	s_waitcnt lgkmcnt(0)

;     float wv[32];
; #pragma unroll
;     for (int i = 0; i < 32; ++i) { const int kk = 2 * i + (lane >> 5); wv[i] = __builtin_nontemporal_load(W + (size_t)(k0 + kk) * ldw + src_c0 + (lane & 31)); }
; #pragma unroll
;     for (int i = 0; i < 32; ++i) { const int kk = 2 * i + (lane >> 5); float w = wv[i] * cscale; if (kgain) w *= kgain[k0 + kk]; scr[kk * 33 + (lane & 31)] = w; }
;     ...
;         if (r < I_BR) { const int kb = r / 32, gi = r % 32; tr_item(F.w_bmm, D, DH, F.Wbr_t + (size_t)2 * D * DH, 32 * gi, 32 * gi, 64 * kb, scr, F.lane); continue; } r -= I_BR;
.LBB0_305:
	s_andn2_b64 vcc, exec, s[2:3]
	s_cbranch_vccnz .LBB0_307
	s_and_b32 s2, s15, 0x7c0
	s_addk_i32 s2, 0xfc00
	s_and_b32 s4, s14, 0x3e0
	v_or_b32_e32 v2, s2, v48
	s_lshl_b32 s8, s4, 2
	v_or_b32_e32 v32, 2, v2
	v_mov_b32_e32 v33, v3
	v_or_b32_e32 v34, 4, v2
	v_mov_b32_e32 v35, v3
	v_or_b32_e32 v36, 6, v2
	v_mov_b32_e32 v37, v3
	v_or_b32_e32 v38, 8, v2
	v_mov_b32_e32 v39, v3
	v_or_b32_e32 v40, 10, v2
	v_mov_b32_e32 v41, v3
	v_or_b32_e32 v42, 12, v2
	v_mov_b32_e32 v43, v3
	v_lshl_add_u64 v[28:29], v[16:17], 0, s[8:9]
	v_lshlrev_b64 v[30:31], 12, v[2:3]
	v_lshlrev_b64 v[32:33], 12, v[32:33]
	v_lshlrev_b64 v[34:35], 12, v[34:35]
	v_lshlrev_b64 v[36:37], 12, v[36:37]
	v_lshlrev_b64 v[38:39], 12, v[38:39]
	v_lshlrev_b64 v[40:41], 12, v[40:41]
	v_lshlrev_b64 v[42:43], 12, v[42:43]
	v_or_b32_e32 v44, 14, v2
	v_mov_b32_e32 v45, v3
	v_lshl_add_u64 v[30:31], v[28:29], 0, v[30:31]
	v_lshl_add_u64 v[32:33], v[28:29], 0, v[32:33]
	v_lshl_add_u64 v[34:35], v[28:29], 0, v[34:35]
	v_lshl_add_u64 v[36:37], v[28:29], 0, v[36:37]
	v_lshl_add_u64 v[38:39], v[28:29], 0, v[38:39]
	v_lshl_add_u64 v[40:41], v[28:29], 0, v[40:41]
	v_lshl_add_u64 v[42:43], v[28:29], 0, v[42:43]
	v_lshlrev_b64 v[44:45], 12, v[44:45]
	v_lshl_add_u64 v[44:45], v[28:29], 0, v[44:45]
	global_load_dword v46, v[30:31], off nt
	global_load_dword v47, v[32:33], off nt
	global_load_dword v68, v[34:35], off nt
	global_load_dword v69, v[36:37], off nt
	global_load_dword v70, v[38:39], off nt
	global_load_dword v71, v[40:41], off nt
	global_load_dword v72, v[42:43], off nt
	global_load_dword v73, v[44:45], off nt
	v_or_b32_e32 v30, 16, v2
	v_mov_b32_e32 v31, v3
	v_or_b32_e32 v32, 18, v2
	v_mov_b32_e32 v33, v3
	v_or_b32_e32 v34, 20, v2
	v_mov_b32_e32 v35, v3
	v_or_b32_e32 v36, 22, v2
	v_mov_b32_e32 v37, v3
	v_or_b32_e32 v38, 24, v2
	v_mov_b32_e32 v39, v3
	v_or_b32_e32 v40, 26, v2
	v_mov_b32_e32 v41, v3
	v_or_b32_e32 v42, 28, v2
	v_mov_b32_e32 v43, v3
	v_lshlrev_b64 v[30:31], 12, v[30:31]
	v_lshlrev_b64 v[32:33], 12, v[32:33]
	v_lshlrev_b64 v[34:35], 12, v[34:35]
	v_lshlrev_b64 v[36:37], 12, v[36:37]
	v_lshlrev_b64 v[38:39], 12, v[38:39]
	v_lshlrev_b64 v[40:41], 12, v[40:41]
	v_lshlrev_b64 v[42:43], 12, v[42:43]
	v_or_b32_e32 v44, 30, v2
	v_mov_b32_e32 v45, v3
	v_lshl_add_u64 v[30:31], v[28:29], 0, v[30:31]
	v_lshl_add_u64 v[32:33], v[28:29], 0, v[32:33]
	v_lshl_add_u64 v[34:35], v[28:29], 0, v[34:35]
	v_lshl_add_u64 v[36:37], v[28:29], 0, v[36:37]
	v_lshl_add_u64 v[38:39], v[28:29], 0, v[38:39]
	v_lshl_add_u64 v[40:41], v[28:29], 0, v[40:41]
	v_lshl_add_u64 v[42:43], v[28:29], 0, v[42:43]
	v_lshlrev_b64 v[44:45], 12, v[44:45]
	v_lshl_add_u64 v[44:45], v[28:29], 0, v[44:45]
	global_load_dword v74, v[30:31], off nt
	global_load_dword v75, v[32:33], off nt
	global_load_dword v76, v[34:35], off nt
	global_load_dword v77, v[36:37], off nt
	global_load_dword v78, v[38:39], off nt
	global_load_dword v79, v[40:41], off nt
	global_load_dword v80, v[42:43], off nt
	global_load_dword v81, v[44:45], off nt
	v_or_b32_e32 v30, 32, v2
	v_mov_b32_e32 v31, v3
	v_or_b32_e32 v32, 34, v2
	v_mov_b32_e32 v33, v3
	v_or_b32_e32 v34, 36, v2
	v_mov_b32_e32 v35, v3
	v_or_b32_e32 v36, 38, v2
	v_mov_b32_e32 v37, v3
	v_or_b32_e32 v38, 40, v2
	v_mov_b32_e32 v39, v3
	v_or_b32_e32 v40, 42, v2
	v_mov_b32_e32 v41, v3
	v_or_b32_e32 v42, 44, v2
	v_mov_b32_e32 v43, v3
	v_lshlrev_b64 v[30:31], 12, v[30:31]
	v_lshlrev_b64 v[32:33], 12, v[32:33]
	v_lshlrev_b64 v[34:35], 12, v[34:35]
	v_lshlrev_b64 v[36:37], 12, v[36:37]
	v_lshlrev_b64 v[38:39], 12, v[38:39]
	v_lshlrev_b64 v[40:41], 12, v[40:41]
	v_lshlrev_b64 v[42:43], 12, v[42:43]
	v_or_b32_e32 v44, 46, v2
	v_mov_b32_e32 v45, v3
	v_lshl_add_u64 v[30:31], v[28:29], 0, v[30:31]
	v_lshl_add_u64 v[32:33], v[28:29], 0, v[32:33]
	v_lshl_add_u64 v[34:35], v[28:29], 0, v[34:35]
	v_lshl_add_u64 v[36:37], v[28:29], 0, v[36:37]
	v_lshl_add_u64 v[38:39], v[28:29], 0, v[38:39]
	v_lshl_add_u64 v[40:41], v[28:29], 0, v[40:41]
	v_lshl_add_u64 v[42:43], v[28:29], 0, v[42:43]
	v_lshlrev_b64 v[44:45], 12, v[44:45]
	v_lshl_add_u64 v[44:45], v[28:29], 0, v[44:45]
	global_load_dword v82, v[30:31], off nt
	global_load_dword v83, v[32:33], off nt
	global_load_dword v84, v[34:35], off nt
	global_load_dword v85, v[36:37], off nt
	global_load_dword v86, v[38:39], off nt
	global_load_dword v87, v[40:41], off nt
	global_load_dword v88, v[42:43], off nt
	global_load_dword v89, v[44:45], off nt
	v_or_b32_e32 v30, 48, v2
	v_mov_b32_e32 v31, v3
	v_or_b32_e32 v32, 50, v2
	v_mov_b32_e32 v33, v3
	v_or_b32_e32 v34, 52, v2
	v_mov_b32_e32 v35, v3
	v_or_b32_e32 v36, 54, v2
	v_mov_b32_e32 v37, v3
	v_or_b32_e32 v38, 56, v2
	v_mov_b32_e32 v39, v3
	v_or_b32_e32 v40, 58, v2
	v_mov_b32_e32 v41, v3
	v_or_b32_e32 v42, 60, v2
	v_mov_b32_e32 v43, v3
	v_or_b32_e32 v2, 62, v2
	v_lshlrev_b64 v[30:31], 12, v[30:31]
	v_lshlrev_b64 v[32:33], 12, v[32:33]
	v_lshlrev_b64 v[34:35], 12, v[34:35]
	v_lshlrev_b64 v[36:37], 12, v[36:37]
	v_lshlrev_b64 v[38:39], 12, v[38:39]
	v_lshlrev_b64 v[40:41], 12, v[40:41]
	v_lshlrev_b64 v[42:43], 12, v[42:43]
	v_lshlrev_b64 v[44:45], 12, v[2:3]
	v_lshl_add_u64 v[30:31], v[28:29], 0, v[30:31]
	v_lshl_add_u64 v[32:33], v[28:29], 0, v[32:33]
	v_lshl_add_u64 v[34:35], v[28:29], 0, v[34:35]
	v_lshl_add_u64 v[36:37], v[28:29], 0, v[36:37]
	v_lshl_add_u64 v[38:39], v[28:29], 0, v[38:39]
	v_lshl_add_u64 v[40:41], v[28:29], 0, v[40:41]
	v_lshl_add_u64 v[42:43], v[28:29], 0, v[42:43]
	v_lshl_add_u64 v[28:29], v[28:29], 0, v[44:45]
	global_load_dword v2, v[30:31], off nt
	s_nop 0
	global_load_dword v30, v[32:33], off nt
	global_load_dword v31, v[34:35], off nt
	s_nop 0
	global_load_dword v32, v[36:37], off nt
	global_load_dword v33, v[38:39], off nt
	global_load_dword v34, v[40:41], off nt
	global_load_dword v35, v[42:43], off nt
	s_nop 0
	global_load_dword v28, v[28:29], off nt
	s_waitcnt vmcnt(30)
; #define GAS __attribute__((address_space(1)))
; #define LAS __attribute__((address_space(3)))
; #define LDS_WAIT() asm volatile("s_waitcnt lgkmcnt(0)" ::: "memory")
; __device__ __forceinline__ unsigned pk2(float lo, float hi) { return f2bf(lo) | (f2bf(hi) << 16); }
;     ...
;     for (int i = 0; i < 32; ++i) { const int kk = 2 * i + (lane >> 5); wv[i] = __builtin_nontemporal_load(W + (size_t)(k0 + kk) * ldw + src_c0 + (lane & 31)); }
; #pragma unroll
;     for (int i = 0; i < 32; ++i) { const int kk = 2 * i + (lane >> 5); float w = wv[i] * cscale; if (kgain) w *= kgain[k0 + kk]; scr[kk * 33 + (lane & 31)] = w; }
;     LDS_WAIT(); asm volatile("" ::: "memory");
;     const int c = lane & 7;
; #pragma unroll
;     for (int j = 0; j < 4; ++j) { const int n = (lane >> 3) + 8 * j; const LAS float* s = scr + (8 * c) * 33 + n;
;         v4u o; o.x = pk2(s[0 * 33], s[1 * 33]); o.y = pk2(s[2 * 33], s[3 * 33]); o.z = pk2(s[4 * 33], s[5 * 33]); o.w = pk2(s[6 * 33], s[7 * 33]);
;         *(GAS v4u*)(WT + (size_t)(dst_r0 + n) * K + k0 + 8 * c) = o; }
;     LDS_WAIT(); asm volatile("" ::: "memory");
	ds_write2_b32 v49, v46, v47 offset1:66
	s_waitcnt vmcnt(28)
	ds_write2_b32 v49, v68, v69 offset0:132 offset1:198
	s_waitcnt vmcnt(26)
	ds_write2_b32 v58, v70, v71 offset0:8 offset1:74
	s_waitcnt vmcnt(24)
	ds_write2_b32 v58, v72, v73 offset0:140 offset1:206
	s_waitcnt vmcnt(22)
	ds_write2_b32 v59, v74, v75 offset0:16 offset1:82
	s_waitcnt vmcnt(20)
	ds_write2_b32 v59, v76, v77 offset0:148 offset1:214
	s_waitcnt vmcnt(18)
	ds_write2_b32 v60, v78, v79 offset0:24 offset1:90
	s_waitcnt vmcnt(16)
	ds_write2_b32 v60, v80, v81 offset0:156 offset1:222
	s_waitcnt vmcnt(14)
	ds_write2_b32 v61, v82, v83 offset0:32 offset1:98
	s_waitcnt vmcnt(12)
	ds_write2_b32 v61, v84, v85 offset0:164 offset1:230
	s_waitcnt vmcnt(10)
	ds_write2_b32 v62, v86, v87 offset0:40 offset1:106
	s_waitcnt vmcnt(8)
	ds_write2_b32 v62, v88, v89 offset0:172 offset1:238
	s_waitcnt vmcnt(6)
	ds_write2_b32 v63, v2, v30 offset0:48 offset1:114
	s_waitcnt vmcnt(4)
	ds_write2_b32 v63, v31, v32 offset0:180 offset1:246
	s_waitcnt vmcnt(2)
	ds_write2_b32 v64, v33, v34 offset0:56 offset1:122
	s_waitcnt vmcnt(0)
	ds_write2_b32 v64, v35, v28 offset0:188 offset1:254
	s_waitcnt lgkmcnt(0)
	ds_read2_b32 v[32:33], v51 offset1:8
	ds_read2_b32 v[36:37], v51 offset0:33 offset1:41
	ds_read2_b32 v[38:39], v51 offset0:66 offset1:74
	ds_read2_b32 v[40:41], v51 offset0:99 offset1:107
	ds_read2_b32 v[42:43], v51 offset0:132 offset1:140
	s_waitcnt lgkmcnt(4)
	v_bfe_u32 v2, v32, 16, 1
	v_add3_u32 v2, v32, v2, s19
	s_waitcnt lgkmcnt(3)
	v_bfe_u32 v28, v36, 16, 1
	v_lshrrev_b32_e32 v2, 16, v2
	v_add3_u32 v28, v36, v28, s19
	ds_read2_b32 v[44:45], v51 offset0:165 offset1:173
	v_and_or_b32 v28, v28, s20, v2
	s_waitcnt lgkmcnt(3)
	v_bfe_u32 v2, v38, 16, 1
	v_add3_u32 v2, v38, v2, s19
	s_waitcnt lgkmcnt(2)
	v_bfe_u32 v29, v40, 16, 1
	ds_read2_b32 v[46:47], v51 offset0:198 offset1:206
	v_lshrrev_b32_e32 v2, 16, v2
	v_add3_u32 v29, v40, v29, s19
	ds_read2_b32 v[68:69], v51 offset0:231 offset1:239
	v_and_or_b32 v29, v29, s20, v2
	s_waitcnt lgkmcnt(3)
	v_bfe_u32 v2, v42, 16, 1
	v_add3_u32 v2, v42, v2, s19
	s_waitcnt lgkmcnt(2)
	v_bfe_u32 v30, v44, 16, 1
	v_lshrrev_b32_e32 v2, 16, v2
	v_add3_u32 v30, v44, v30, s19
	v_and_or_b32 v30, v30, s20, v2
	s_waitcnt lgkmcnt(1)
	v_bfe_u32 v2, v46, 16, 1
	v_add3_u32 v2, v46, v2, s19
	s_waitcnt lgkmcnt(0)
	v_bfe_u32 v31, v68, 16, 1
	v_lshrrev_b32_e32 v2, 16, v2
	v_add3_u32 v31, v68, v31, s19
	s_mov_b32 s3, s9
	v_and_or_b32 v31, v31, s20, v2
	v_or_b32_e32 v2, s4, v50
	v_lshl_add_u64 v[34:35], s[2:3], 1, v[18:19]
	v_lshlrev_b32_e32 v2, 10, v2
	v_lshl_add_u64 v[70:71], v[34:35], 0, v[2:3]
	v_bfe_u32 v2, v33, 16, 1
	global_store_dwordx4 v[70:71], v[28:31], off sc1
	v_add3_u32 v2, v33, v2, s19
	v_lshrrev_b32_e32 v2, 16, v2
	v_bfe_u32 v28, v37, 16, 1
	v_add3_u32 v28, v37, v28, s19
	v_and_or_b32 v28, v28, s20, v2
	v_bfe_u32 v2, v39, 16, 1
	v_add3_u32 v2, v39, v2, s19
	v_bfe_u32 v29, v41, 16, 1
	v_lshrrev_b32_e32 v2, 16, v2
	v_add3_u32 v29, v41, v29, s19
	v_and_or_b32 v29, v29, s20, v2
	v_bfe_u32 v2, v43, 16, 1
	v_add3_u32 v2, v43, v2, s19
	v_bfe_u32 v30, v45, 16, 1
	v_lshrrev_b32_e32 v2, 16, v2
	v_add3_u32 v30, v45, v30, s19
	v_and_or_b32 v30, v30, s20, v2
	v_bfe_u32 v2, v47, 16, 1
	v_add3_u32 v2, v47, v2, s19
	v_bfe_u32 v31, v69, 16, 1
	v_lshrrev_b32_e32 v2, 16, v2
	v_add3_u32 v31, v69, v31, s19
	v_and_or_b32 v31, v31, s20, v2
	v_or_b32_e32 v2, s4, v52
	v_lshlrev_b32_e32 v2, 10, v2
	ds_read2_b32 v[32:33], v51 offset0:16 offset1:24
	v_lshl_add_u64 v[36:37], v[34:35], 0, v[2:3]
	global_store_dwordx4 v[36:37], v[28:31], off sc1
	ds_read2_b32 v[36:37], v51 offset0:49 offset1:57
	ds_read2_b32 v[38:39], v51 offset0:82 offset1:90
	ds_read2_b32 v[40:41], v51 offset0:115 offset1:123
	s_waitcnt lgkmcnt(3)
	v_bfe_u32 v2, v32, 16, 1
	v_add3_u32 v2, v32, v2, s19
	s_waitcnt lgkmcnt(2)
	v_bfe_u32 v28, v36, 16, 1
	ds_read2_b32 v[42:43], v51 offset0:148 offset1:156
	v_lshrrev_b32_e32 v2, 16, v2
	v_add3_u32 v28, v36, v28, s19
	ds_read2_b32 v[44:45], v51 offset0:181 offset1:189
	v_and_or_b32 v28, v28, s20, v2
	s_waitcnt lgkmcnt(3)
	v_bfe_u32 v2, v38, 16, 1
	v_add3_u32 v2, v38, v2, s19
	s_waitcnt lgkmcnt(2)
	v_bfe_u32 v29, v40, 16, 1
	ds_read2_b32 v[46:47], v51 offset0:214 offset1:222
	v_lshrrev_b32_e32 v2, 16, v2
	v_add3_u32 v29, v40, v29, s19
	ds_read2_b32 v[68:69], v51 offset0:247 offset1:255
	v_and_or_b32 v29, v29, s20, v2
	s_waitcnt lgkmcnt(3)
	v_bfe_u32 v2, v42, 16, 1
	v_add3_u32 v2, v42, v2, s19
	s_waitcnt lgkmcnt(2)
	v_bfe_u32 v30, v44, 16, 1
	v_lshrrev_b32_e32 v2, 16, v2
	v_add3_u32 v30, v44, v30, s19
	v_and_or_b32 v30, v30, s20, v2
	s_waitcnt lgkmcnt(1)
	v_bfe_u32 v2, v46, 16, 1
	v_add3_u32 v2, v46, v2, s19
	s_waitcnt lgkmcnt(0)
	v_bfe_u32 v31, v68, 16, 1
	v_lshrrev_b32_e32 v2, 16, v2
	v_add3_u32 v31, v68, v31, s19
	v_and_or_b32 v31, v31, s20, v2
	v_or_b32_e32 v2, s4, v53
	v_lshlrev_b32_e32 v2, 10, v2
	v_lshl_add_u64 v[70:71], v[34:35], 0, v[2:3]
	v_bfe_u32 v2, v33, 16, 1
	global_store_dwordx4 v[70:71], v[28:31], off sc1
	v_add3_u32 v2, v33, v2, s19
	v_lshrrev_b32_e32 v2, 16, v2
	v_bfe_u32 v28, v37, 16, 1
	v_add3_u32 v28, v37, v28, s19
	v_and_or_b32 v28, v28, s20, v2
	v_bfe_u32 v2, v39, 16, 1
	v_add3_u32 v2, v39, v2, s19
	v_bfe_u32 v29, v41, 16, 1
	v_lshrrev_b32_e32 v2, 16, v2
	v_add3_u32 v29, v41, v29, s19
	v_and_or_b32 v29, v29, s20, v2
	v_bfe_u32 v2, v43, 16, 1
	v_add3_u32 v2, v43, v2, s19
	v_bfe_u32 v30, v45, 16, 1
	v_lshrrev_b32_e32 v2, 16, v2
	v_add3_u32 v30, v45, v30, s19
	v_and_or_b32 v30, v30, s20, v2
	v_bfe_u32 v2, v47, 16, 1
	v_add3_u32 v2, v47, v2, s19
	v_bfe_u32 v31, v69, 16, 1
	v_lshrrev_b32_e32 v2, 16, v2
	v_add3_u32 v31, v69, v31, s19
	v_and_or_b32 v31, v31, s20, v2
	v_or_b32_e32 v2, s4, v54
	v_lshlrev_b32_e32 v2, 10, v2
	v_lshl_add_u64 v[32:33], v[34:35], 0, v[2:3]
	global_store_dwordx4 v[32:33], v[28:31], off sc1
	s_waitcnt lgkmcnt(0)

;     ...
;     for (int i = 0; i < 32; ++i) { const int kk = 2 * i + (lane >> 5); wv[i] = __builtin_nontemporal_load(W + (size_t)(k0 + kk) * ldw + src_c0 + (lane & 31)); }
; #pragma unroll
;     for (int i = 0; i < 32; ++i) { const int kk = 2 * i + (lane >> 5); float w = wv[i] * cscale; if (kgain) w *= kgain[k0 + kk]; scr[kk * 33 + (lane & 31)] = w; }
;     ...
;         if (r < I_BR) { const int kb = r / 32, gi = r % 32; tr_item(F.w_bsb, D, DH, F.Wbr_t, 32 * gi, 32 * gi, 64 * kb, scr, F.lane); continue; } r -= I_BR;
;         if (r < I_BR) { const int kb = r / 32, gi = r % 32; tr_item(F.w_bfx, D, DH, F.Wbr_t + (size_t)D * DH, 32 * gi, 32 * gi, 64 * kb, scr, F.lane); continue; } r -= I_BR;
;         if (r < I_BR) { const int kb = r / 32, gi = r % 32; tr_item(F.w_bmm, D, DH, F.Wbr_t + (size_t)2 * D * DH, 32 * gi, 32 * gi, 64 * kb, scr, F.lane); continue; } r -= I_BR;
.LBB0_308:
	s_andn2_b64 vcc, exec, s[2:3]
	s_cbranch_vccnz .LBB0_310
	s_and_b32 s2, s15, 0x3c0
	s_addk_i32 s2, 0xfe00
	s_and_b32 s4, s14, 0x3e0
	v_or_b32_e32 v2, s2, v48
	s_lshl_b32 s8, s4, 2
	v_or_b32_e32 v32, 2, v2
	v_mov_b32_e32 v33, v3
	v_or_b32_e32 v34, 4, v2
	v_mov_b32_e32 v35, v3
	v_or_b32_e32 v36, 6, v2
	v_mov_b32_e32 v37, v3
	v_or_b32_e32 v38, 8, v2
	v_mov_b32_e32 v39, v3
	v_or_b32_e32 v40, 10, v2
	v_mov_b32_e32 v41, v3
	v_or_b32_e32 v42, 12, v2
	v_mov_b32_e32 v43, v3
	v_lshl_add_u64 v[28:29], v[20:21], 0, s[8:9]
	v_lshlrev_b64 v[30:31], 12, v[2:3]
	v_lshlrev_b64 v[32:33], 12, v[32:33]
	v_lshlrev_b64 v[34:35], 12, v[34:35]
	v_lshlrev_b64 v[36:37], 12, v[36:37]
	v_lshlrev_b64 v[38:39], 12, v[38:39]
	v_lshlrev_b64 v[40:41], 12, v[40:41]
	v_lshlrev_b64 v[42:43], 12, v[42:43]
	v_or_b32_e32 v44, 14, v2
	v_mov_b32_e32 v45, v3
	v_lshl_add_u64 v[30:31], v[28:29], 0, v[30:31]
	v_lshl_add_u64 v[32:33], v[28:29], 0, v[32:33]
	v_lshl_add_u64 v[34:35], v[28:29], 0, v[34:35]
	v_lshl_add_u64 v[36:37], v[28:29], 0, v[36:37]
	v_lshl_add_u64 v[38:39], v[28:29], 0, v[38:39]
	v_lshl_add_u64 v[40:41], v[28:29], 0, v[40:41]
	v_lshl_add_u64 v[42:43], v[28:29], 0, v[42:43]
	v_lshlrev_b64 v[44:45], 12, v[44:45]
	v_lshl_add_u64 v[44:45], v[28:29], 0, v[44:45]
	global_load_dword v46, v[30:31], off nt
	global_load_dword v47, v[32:33], off nt
	global_load_dword v68, v[34:35], off nt
	global_load_dword v69, v[36:37], off nt
	global_load_dword v70, v[38:39], off nt
	global_load_dword v71, v[40:41], off nt
	global_load_dword v72, v[42:43], off nt
	global_load_dword v73, v[44:45], off nt
	v_or_b32_e32 v30, 16, v2
	v_mov_b32_e32 v31, v3
	v_or_b32_e32 v32, 18, v2
	v_mov_b32_e32 v33, v3
	v_or_b32_e32 v34, 20, v2
	v_mov_b32_e32 v35, v3
	v_or_b32_e32 v36, 22, v2
	v_mov_b32_e32 v37, v3
	v_or_b32_e32 v38, 24, v2
	v_mov_b32_e32 v39, v3
	v_or_b32_e32 v40, 26, v2
	v_mov_b32_e32 v41, v3
	v_or_b32_e32 v42, 28, v2
	v_mov_b32_e32 v43, v3
	v_lshlrev_b64 v[30:31], 12, v[30:31]
	v_lshlrev_b64 v[32:33], 12, v[32:33]
	v_lshlrev_b64 v[34:35], 12, v[34:35]
	v_lshlrev_b64 v[36:37], 12, v[36:37]
	v_lshlrev_b64 v[38:39], 12, v[38:39]
	v_lshlrev_b64 v[40:41], 12, v[40:41]
	v_lshlrev_b64 v[42:43], 12, v[42:43]
	v_or_b32_e32 v44, 30, v2
	v_mov_b32_e32 v45, v3
	v_lshl_add_u64 v[30:31], v[28:29], 0, v[30:31]
	v_lshl_add_u64 v[32:33], v[28:29], 0, v[32:33]
	v_lshl_add_u64 v[34:35], v[28:29], 0, v[34:35]
	v_lshl_add_u64 v[36:37], v[28:29], 0, v[36:37]
	v_lshl_add_u64 v[38:39], v[28:29], 0, v[38:39]
	v_lshl_add_u64 v[40:41], v[28:29], 0, v[40:41]
	v_lshl_add_u64 v[42:43], v[28:29], 0, v[42:43]
	v_lshlrev_b64 v[44:45], 12, v[44:45]
	v_lshl_add_u64 v[44:45], v[28:29], 0, v[44:45]
	global_load_dword v74, v[30:31], off nt
	global_load_dword v75, v[32:33], off nt
	global_load_dword v76, v[34:35], off nt
	global_load_dword v77, v[36:37], off nt
	global_load_dword v78, v[38:39], off nt
	global_load_dword v79, v[40:41], off nt
	global_load_dword v80, v[42:43], off nt
	global_load_dword v81, v[44:45], off nt
	v_or_b32_e32 v30, 32, v2
	v_mov_b32_e32 v31, v3
	v_or_b32_e32 v32, 34, v2
	v_mov_b32_e32 v33, v3
	v_or_b32_e32 v34, 36, v2
	v_mov_b32_e32 v35, v3
	v_or_b32_e32 v36, 38, v2
	v_mov_b32_e32 v37, v3
	v_or_b32_e32 v38, 40, v2
	v_mov_b32_e32 v39, v3
	v_or_b32_e32 v40, 42, v2
	v_mov_b32_e32 v41, v3
	v_or_b32_e32 v42, 44, v2
	v_mov_b32_e32 v43, v3
	v_lshlrev_b64 v[30:31], 12, v[30:31]
	v_lshlrev_b64 v[32:33], 12, v[32:33]
	v_lshlrev_b64 v[34:35], 12, v[34:35]
	v_lshlrev_b64 v[36:37], 12, v[36:37]
	v_lshlrev_b64 v[38:39], 12, v[38:39]
	v_lshlrev_b64 v[40:41], 12, v[40:41]
	v_lshlrev_b64 v[42:43], 12, v[42:43]
	v_or_b32_e32 v44, 46, v2
	v_mov_b32_e32 v45, v3
	v_lshl_add_u64 v[30:31], v[28:29], 0, v[30:31]
	v_lshl_add_u64 v[32:33], v[28:29], 0, v[32:33]
	v_lshl_add_u64 v[34:35], v[28:29], 0, v[34:35]
	v_lshl_add_u64 v[36:37], v[28:29], 0, v[36:37]
	v_lshl_add_u64 v[38:39], v[28:29], 0, v[38:39]
	v_lshl_add_u64 v[40:41], v[28:29], 0, v[40:41]
	v_lshl_add_u64 v[42:43], v[28:29], 0, v[42:43]
	v_lshlrev_b64 v[44:45], 12, v[44:45]
	v_lshl_add_u64 v[44:45], v[28:29], 0, v[44:45]
	global_load_dword v82, v[30:31], off nt
	global_load_dword v83, v[32:33], off nt
	global_load_dword v84, v[34:35], off nt
	global_load_dword v85, v[36:37], off nt
	global_load_dword v86, v[38:39], off nt
	global_load_dword v87, v[40:41], off nt
	global_load_dword v88, v[42:43], off nt
	global_load_dword v89, v[44:45], off nt
	v_or_b32_e32 v30, 48, v2
	v_mov_b32_e32 v31, v3
	v_or_b32_e32 v32, 50, v2
	v_mov_b32_e32 v33, v3
	v_or_b32_e32 v34, 52, v2
	v_mov_b32_e32 v35, v3
	v_or_b32_e32 v36, 54, v2
	v_mov_b32_e32 v37, v3
	v_or_b32_e32 v38, 56, v2
	v_mov_b32_e32 v39, v3
	v_or_b32_e32 v40, 58, v2
	v_mov_b32_e32 v41, v3
	v_or_b32_e32 v42, 60, v2
	v_mov_b32_e32 v43, v3
	v_or_b32_e32 v2, 62, v2
	v_lshlrev_b64 v[30:31], 12, v[30:31]
	v_lshlrev_b64 v[32:33], 12, v[32:33]
	v_lshlrev_b64 v[34:35], 12, v[34:35]
	v_lshlrev_b64 v[36:37], 12, v[36:37]
	v_lshlrev_b64 v[38:39], 12, v[38:39]
	v_lshlrev_b64 v[40:41], 12, v[40:41]
	v_lshlrev_b64 v[42:43], 12, v[42:43]
	v_lshlrev_b64 v[44:45], 12, v[2:3]
	v_lshl_add_u64 v[30:31], v[28:29], 0, v[30:31]
	v_lshl_add_u64 v[32:33], v[28:29], 0, v[32:33]
	v_lshl_add_u64 v[34:35], v[28:29], 0, v[34:35]
	v_lshl_add_u64 v[36:37], v[28:29], 0, v[36:37]
	v_lshl_add_u64 v[38:39], v[28:29], 0, v[38:39]
	v_lshl_add_u64 v[40:41], v[28:29], 0, v[40:41]
	v_lshl_add_u64 v[42:43], v[28:29], 0, v[42:43]
	v_lshl_add_u64 v[28:29], v[28:29], 0, v[44:45]
	global_load_dword v2, v[30:31], off nt
	s_nop 0
	global_load_dword v30, v[32:33], off nt
	global_load_dword v31, v[34:35], off nt
	s_nop 0
	global_load_dword v32, v[36:37], off nt
	global_load_dword v33, v[38:39], off nt
	global_load_dword v34, v[40:41], off nt
	global_load_dword v35, v[42:43], off nt
	s_nop 0
	global_load_dword v28, v[28:29], off nt
	s_waitcnt vmcnt(30)
; #define GAS __attribute__((address_space(1)))
; #define LAS __attribute__((address_space(3)))
; #define LDS_WAIT() asm volatile("s_waitcnt lgkmcnt(0)" ::: "memory")
; __device__ __forceinline__ unsigned pk2(float lo, float hi) { return f2bf(lo) | (f2bf(hi) << 16); }
;     ...
;     for (int i = 0; i < 32; ++i) { const int kk = 2 * i + (lane >> 5); wv[i] = __builtin_nontemporal_load(W + (size_t)(k0 + kk) * ldw + src_c0 + (lane & 31)); }
; #pragma unroll
;     for (int i = 0; i < 32; ++i) { const int kk = 2 * i + (lane >> 5); float w = wv[i] * cscale; if (kgain) w *= kgain[k0 + kk]; scr[kk * 33 + (lane & 31)] = w; }
;     LDS_WAIT(); asm volatile("" ::: "memory");
;     const int c = lane & 7;
; #pragma unroll
;     for (int j = 0; j < 4; ++j) { const int n = (lane >> 3) + 8 * j; const LAS float* s = scr + (8 * c) * 33 + n;
;         v4u o; o.x = pk2(s[0 * 33], s[1 * 33]); o.y = pk2(s[2 * 33], s[3 * 33]); o.z = pk2(s[4 * 33], s[5 * 33]); o.w = pk2(s[6 * 33], s[7 * 33]);
;         *(GAS v4u*)(WT + (size_t)(dst_r0 + n) * K + k0 + 8 * c) = o; }
;     LDS_WAIT(); asm volatile("" ::: "memory");
	ds_write2_b32 v49, v46, v47 offset1:66
	s_waitcnt vmcnt(28)
	ds_write2_b32 v49, v68, v69 offset0:132 offset1:198
	s_waitcnt vmcnt(26)
	ds_write2_b32 v58, v70, v71 offset0:8 offset1:74
	s_waitcnt vmcnt(24)
	ds_write2_b32 v58, v72, v73 offset0:140 offset1:206
	s_waitcnt vmcnt(22)
	ds_write2_b32 v59, v74, v75 offset0:16 offset1:82
	s_waitcnt vmcnt(20)
	ds_write2_b32 v59, v76, v77 offset0:148 offset1:214
	s_waitcnt vmcnt(18)
	ds_write2_b32 v60, v78, v79 offset0:24 offset1:90
	s_waitcnt vmcnt(16)
	ds_write2_b32 v60, v80, v81 offset0:156 offset1:222
	s_waitcnt vmcnt(14)
	ds_write2_b32 v61, v82, v83 offset0:32 offset1:98
	s_waitcnt vmcnt(12)
	ds_write2_b32 v61, v84, v85 offset0:164 offset1:230
	s_waitcnt vmcnt(10)
	ds_write2_b32 v62, v86, v87 offset0:40 offset1:106
	s_waitcnt vmcnt(8)
	ds_write2_b32 v62, v88, v89 offset0:172 offset1:238
	s_waitcnt vmcnt(6)
	ds_write2_b32 v63, v2, v30 offset0:48 offset1:114
	s_waitcnt vmcnt(4)
	ds_write2_b32 v63, v31, v32 offset0:180 offset1:246
	s_waitcnt vmcnt(2)
	ds_write2_b32 v64, v33, v34 offset0:56 offset1:122
	s_waitcnt vmcnt(0)
	ds_write2_b32 v64, v35, v28 offset0:188 offset1:254
	s_waitcnt lgkmcnt(0)
	ds_read2_b32 v[32:33], v51 offset1:8
	ds_read2_b32 v[36:37], v51 offset0:33 offset1:41
	ds_read2_b32 v[38:39], v51 offset0:66 offset1:74
	ds_read2_b32 v[40:41], v51 offset0:99 offset1:107
	ds_read2_b32 v[42:43], v51 offset0:132 offset1:140
	s_waitcnt lgkmcnt(4)
	v_bfe_u32 v2, v32, 16, 1
	v_add3_u32 v2, v32, v2, s19
	s_waitcnt lgkmcnt(3)
	v_bfe_u32 v28, v36, 16, 1
	v_lshrrev_b32_e32 v2, 16, v2
	v_add3_u32 v28, v36, v28, s19
	ds_read2_b32 v[44:45], v51 offset0:165 offset1:173
	v_and_or_b32 v28, v28, s20, v2
	s_waitcnt lgkmcnt(3)
	v_bfe_u32 v2, v38, 16, 1
	v_add3_u32 v2, v38, v2, s19
	s_waitcnt lgkmcnt(2)
	v_bfe_u32 v29, v40, 16, 1
	ds_read2_b32 v[46:47], v51 offset0:198 offset1:206
	v_lshrrev_b32_e32 v2, 16, v2
	v_add3_u32 v29, v40, v29, s19
	ds_read2_b32 v[68:69], v51 offset0:231 offset1:239
	v_and_or_b32 v29, v29, s20, v2
	s_waitcnt lgkmcnt(3)
	v_bfe_u32 v2, v42, 16, 1
	v_add3_u32 v2, v42, v2, s19
	s_waitcnt lgkmcnt(2)
	v_bfe_u32 v30, v44, 16, 1
	v_lshrrev_b32_e32 v2, 16, v2
	v_add3_u32 v30, v44, v30, s19
	v_and_or_b32 v30, v30, s20, v2
	s_waitcnt lgkmcnt(1)
	v_bfe_u32 v2, v46, 16, 1
	v_add3_u32 v2, v46, v2, s19
	s_waitcnt lgkmcnt(0)
	v_bfe_u32 v31, v68, 16, 1
	v_lshrrev_b32_e32 v2, 16, v2
	v_add3_u32 v31, v68, v31, s19
	s_mov_b32 s3, s9
	v_and_or_b32 v31, v31, s20, v2
	v_or_b32_e32 v2, s4, v50
	v_lshl_add_u64 v[34:35], s[2:3], 1, v[22:23]
	v_lshlrev_b32_e32 v2, 10, v2
	v_lshl_add_u64 v[70:71], v[34:35], 0, v[2:3]
	v_bfe_u32 v2, v33, 16, 1
	global_store_dwordx4 v[70:71], v[28:31], off sc1
	v_add3_u32 v2, v33, v2, s19
	v_lshrrev_b32_e32 v2, 16, v2
	v_bfe_u32 v28, v37, 16, 1
	v_add3_u32 v28, v37, v28, s19
	v_and_or_b32 v28, v28, s20, v2
	v_bfe_u32 v2, v39, 16, 1
	v_add3_u32 v2, v39, v2, s19
	v_bfe_u32 v29, v41, 16, 1
	v_lshrrev_b32_e32 v2, 16, v2
	v_add3_u32 v29, v41, v29, s19
	v_and_or_b32 v29, v29, s20, v2
	v_bfe_u32 v2, v43, 16, 1
	v_add3_u32 v2, v43, v2, s19
	v_bfe_u32 v30, v45, 16, 1
	v_lshrrev_b32_e32 v2, 16, v2
	v_add3_u32 v30, v45, v30, s19
	v_and_or_b32 v30, v30, s20, v2
	v_bfe_u32 v2, v47, 16, 1
	v_add3_u32 v2, v47, v2, s19
	v_bfe_u32 v31, v69, 16, 1
	v_lshrrev_b32_e32 v2, 16, v2
	v_add3_u32 v31, v69, v31, s19
	v_and_or_b32 v31, v31, s20, v2
	v_or_b32_e32 v2, s4, v52
	v_lshlrev_b32_e32 v2, 10, v2
	ds_read2_b32 v[32:33], v51 offset0:16 offset1:24
	v_lshl_add_u64 v[36:37], v[34:35], 0, v[2:3]
	global_store_dwordx4 v[36:37], v[28:31], off sc1
	ds_read2_b32 v[36:37], v51 offset0:49 offset1:57
	ds_read2_b32 v[38:39], v51 offset0:82 offset1:90
	ds_read2_b32 v[40:41], v51 offset0:115 offset1:123
	s_waitcnt lgkmcnt(3)
	v_bfe_u32 v2, v32, 16, 1
	v_add3_u32 v2, v32, v2, s19
	s_waitcnt lgkmcnt(2)
	v_bfe_u32 v28, v36, 16, 1
	ds_read2_b32 v[42:43], v51 offset0:148 offset1:156
	v_lshrrev_b32_e32 v2, 16, v2
	v_add3_u32 v28, v36, v28, s19
	ds_read2_b32 v[44:45], v51 offset0:181 offset1:189
	v_and_or_b32 v28, v28, s20, v2
	s_waitcnt lgkmcnt(3)
	v_bfe_u32 v2, v38, 16, 1
	v_add3_u32 v2, v38, v2, s19
	s_waitcnt lgkmcnt(2)
	v_bfe_u32 v29, v40, 16, 1
	ds_read2_b32 v[46:47], v51 offset0:214 offset1:222
	v_lshrrev_b32_e32 v2, 16, v2
	v_add3_u32 v29, v40, v29, s19
	ds_read2_b32 v[68:69], v51 offset0:247 offset1:255
	v_and_or_b32 v29, v29, s20, v2
	s_waitcnt lgkmcnt(3)
	v_bfe_u32 v2, v42, 16, 1
	v_add3_u32 v2, v42, v2, s19
	s_waitcnt lgkmcnt(2)
	v_bfe_u32 v30, v44, 16, 1
	v_lshrrev_b32_e32 v2, 16, v2
	v_add3_u32 v30, v44, v30, s19
	v_and_or_b32 v30, v30, s20, v2
	s_waitcnt lgkmcnt(1)
	v_bfe_u32 v2, v46, 16, 1
	v_add3_u32 v2, v46, v2, s19
	s_waitcnt lgkmcnt(0)
	v_bfe_u32 v31, v68, 16, 1
	v_lshrrev_b32_e32 v2, 16, v2
	v_add3_u32 v31, v68, v31, s19
	v_and_or_b32 v31, v31, s20, v2
	v_or_b32_e32 v2, s4, v53
	v_lshlrev_b32_e32 v2, 10, v2
	v_lshl_add_u64 v[70:71], v[34:35], 0, v[2:3]
	v_bfe_u32 v2, v33, 16, 1
	global_store_dwordx4 v[70:71], v[28:31], off sc1
	v_add3_u32 v2, v33, v2, s19
	v_lshrrev_b32_e32 v2, 16, v2
	v_bfe_u32 v28, v37, 16, 1
	v_add3_u32 v28, v37, v28, s19
	v_and_or_b32 v28, v28, s20, v2
	v_bfe_u32 v2, v39, 16, 1
	v_add3_u32 v2, v39, v2, s19
	v_bfe_u32 v29, v41, 16, 1
	v_lshrrev_b32_e32 v2, 16, v2
	v_add3_u32 v29, v41, v29, s19
	v_and_or_b32 v29, v29, s20, v2
	v_bfe_u32 v2, v43, 16, 1
	v_add3_u32 v2, v43, v2, s19
	v_bfe_u32 v30, v45, 16, 1
	v_lshrrev_b32_e32 v2, 16, v2
	v_add3_u32 v30, v45, v30, s19
	v_and_or_b32 v30, v30, s20, v2
	v_bfe_u32 v2, v47, 16, 1
	v_add3_u32 v2, v47, v2, s19
	v_bfe_u32 v31, v69, 16, 1
	v_lshrrev_b32_e32 v2, 16, v2
	v_add3_u32 v31, v69, v31, s19
	v_and_or_b32 v31, v31, s20, v2
	v_or_b32_e32 v2, s4, v54
	v_lshlrev_b32_e32 v2, 10, v2
	v_lshl_add_u64 v[32:33], v[34:35], 0, v[2:3]
	global_store_dwordx4 v[32:33], v[28:31], off sc1
	s_waitcnt lgkmcnt(0)

;     ...
;     for (int i = 0; i < 32; ++i) { const int kk = 2 * i + (lane >> 5); wv[i] = __builtin_nontemporal_load(W + (size_t)(k0 + kk) * ldw + src_c0 + (lane & 31)); }
; #pragma unroll
;     for (int i = 0; i < 32; ++i) { const int kk = 2 * i + (lane >> 5); float w = wv[i] * cscale; if (kgain) w *= kgain[k0 + kk]; scr[kk * 33 + (lane & 31)] = w; }
;     ...
;         if (r < I_BR) { const int kb = r / 32, gi = r % 32; tr_item(F.w_bsb, D, DH, F.Wbr_t, 32 * gi, 32 * gi, 64 * kb, scr, F.lane); continue; } r -= I_BR;
;         if (r < I_BR) { const int kb = r / 32, gi = r % 32; tr_item(F.w_bfx, D, DH, F.Wbr_t + (size_t)D * DH, 32 * gi, 32 * gi, 64 * kb, scr, F.lane); continue; } r -= I_BR;
;         if (r < I_BR) { const int kb = r / 32, gi = r % 32; tr_item(F.w_bmm, D, DH, F.Wbr_t + (size_t)2 * D * DH, 32 * gi, 32 * gi, 64 * kb, scr, F.lane); continue; } r -= I_BR;
;         if (r < I_OUT) { const int kb = r / 32, gi = r % 32; tr_item(F.w_out, D, D, F.Wout_t, 32 * gi, 32 * gi, 64 * kb, scr, F.lane); continue; } r -= I_OUT;
;         if (r < I_UP) { const int kb = r / 128, gi = r % 128; tr_item(F.w_up, FF, D, F.Wup_t, 32 * gi, 32 * gi, 64 * kb, scr, F.lane, F.g_mlp); continue; } r -= I_UP;
;         { const int kb = r / 32, gi = r % 32; tr_item(F.w_dn, D, FF, F.Wdn_t, 32 * gi, 32 * gi, 64 * kb, scr, F.lane); }
.LBB0_311:
	s_andn2_b64 vcc, exec, s[2:3]
	s_cbranch_vccnz .LBB0_268
	s_and_b32 s3, s15, 0x7fffffc0
	s_and_b32 s2, s14, 0x3e0
	v_or_b32_e32 v2, s3, v48
	s_lshl_b32 s8, s2, 2
	v_or_b32_e32 v32, 2, v2
	v_mov_b32_e32 v33, v3
	v_or_b32_e32 v34, 4, v2
	v_mov_b32_e32 v35, v3
	v_or_b32_e32 v36, 6, v2
	v_mov_b32_e32 v37, v3
	v_or_b32_e32 v38, 8, v2
	v_mov_b32_e32 v39, v3
	v_or_b32_e32 v40, 10, v2
	v_mov_b32_e32 v41, v3
	v_or_b32_e32 v42, 12, v2
	v_mov_b32_e32 v43, v3
	v_lshl_add_u64 v[28:29], v[24:25], 0, s[8:9]
	v_lshlrev_b64 v[30:31], 12, v[2:3]
	v_lshlrev_b64 v[32:33], 12, v[32:33]
	v_lshlrev_b64 v[34:35], 12, v[34:35]
	v_lshlrev_b64 v[36:37], 12, v[36:37]
	v_lshlrev_b64 v[38:39], 12, v[38:39]
	v_lshlrev_b64 v[40:41], 12, v[40:41]
	v_lshlrev_b64 v[42:43], 12, v[42:43]
	v_or_b32_e32 v44, 14, v2
	v_mov_b32_e32 v45, v3
	v_lshl_add_u64 v[30:31], v[28:29], 0, v[30:31]
	v_lshl_add_u64 v[32:33], v[28:29], 0, v[32:33]
	v_lshl_add_u64 v[34:35], v[28:29], 0, v[34:35]
	v_lshl_add_u64 v[36:37], v[28:29], 0, v[36:37]
	v_lshl_add_u64 v[38:39], v[28:29], 0, v[38:39]
	v_lshl_add_u64 v[40:41], v[28:29], 0, v[40:41]
	v_lshl_add_u64 v[42:43], v[28:29], 0, v[42:43]
	v_lshlrev_b64 v[44:45], 12, v[44:45]
	v_lshl_add_u64 v[44:45], v[28:29], 0, v[44:45]
	global_load_dword v46, v[30:31], off nt
	global_load_dword v47, v[32:33], off nt
	global_load_dword v68, v[34:35], off nt
	global_load_dword v69, v[36:37], off nt
	global_load_dword v70, v[38:39], off nt
	global_load_dword v71, v[40:41], off nt
	global_load_dword v72, v[42:43], off nt
	global_load_dword v73, v[44:45], off nt
	v_or_b32_e32 v30, 16, v2
	v_mov_b32_e32 v31, v3
	v_or_b32_e32 v32, 18, v2
	v_mov_b32_e32 v33, v3
	v_or_b32_e32 v34, 20, v2
	v_mov_b32_e32 v35, v3
	v_or_b32_e32 v36, 22, v2
	v_mov_b32_e32 v37, v3
	v_or_b32_e32 v38, 24, v2
	v_mov_b32_e32 v39, v3
	v_or_b32_e32 v40, 26, v2
	v_mov_b32_e32 v41, v3
	v_or_b32_e32 v42, 28, v2
	v_mov_b32_e32 v43, v3
	v_lshlrev_b64 v[30:31], 12, v[30:31]
	v_lshlrev_b64 v[32:33], 12, v[32:33]
	v_lshlrev_b64 v[34:35], 12, v[34:35]
	v_lshlrev_b64 v[36:37], 12, v[36:37]
	v_lshlrev_b64 v[38:39], 12, v[38:39]
	v_lshlrev_b64 v[40:41], 12, v[40:41]
	v_lshlrev_b64 v[42:43], 12, v[42:43]
	v_or_b32_e32 v44, 30, v2
	v_mov_b32_e32 v45, v3
	v_lshl_add_u64 v[30:31], v[28:29], 0, v[30:31]
	v_lshl_add_u64 v[32:33], v[28:29], 0, v[32:33]
	v_lshl_add_u64 v[34:35], v[28:29], 0, v[34:35]
	v_lshl_add_u64 v[36:37], v[28:29], 0, v[36:37]
	v_lshl_add_u64 v[38:39], v[28:29], 0, v[38:39]
	v_lshl_add_u64 v[40:41], v[28:29], 0, v[40:41]
	v_lshl_add_u64 v[42:43], v[28:29], 0, v[42:43]
	v_lshlrev_b64 v[44:45], 12, v[44:45]
	v_lshl_add_u64 v[44:45], v[28:29], 0, v[44:45]
	global_load_dword v74, v[30:31], off nt
	global_load_dword v75, v[32:33], off nt
	global_load_dword v76, v[34:35], off nt
	global_load_dword v77, v[36:37], off nt
	global_load_dword v78, v[38:39], off nt
	global_load_dword v79, v[40:41], off nt
	global_load_dword v80, v[42:43], off nt
	global_load_dword v81, v[44:45], off nt
	v_or_b32_e32 v30, 32, v2
	v_mov_b32_e32 v31, v3
	v_or_b32_e32 v32, 34, v2
	v_mov_b32_e32 v33, v3
	v_or_b32_e32 v34, 36, v2
	v_mov_b32_e32 v35, v3
	v_or_b32_e32 v36, 38, v2
	v_mov_b32_e32 v37, v3
	v_or_b32_e32 v38, 40, v2
	v_mov_b32_e32 v39, v3
	v_or_b32_e32 v40, 42, v2
	v_mov_b32_e32 v41, v3
	v_or_b32_e32 v42, 44, v2
	v_mov_b32_e32 v43, v3
	v_lshlrev_b64 v[30:31], 12, v[30:31]
	v_lshlrev_b64 v[32:33], 12, v[32:33]
	v_lshlrev_b64 v[34:35], 12, v[34:35]
	v_lshlrev_b64 v[36:37], 12, v[36:37]
	v_lshlrev_b64 v[38:39], 12, v[38:39]
	v_lshlrev_b64 v[40:41], 12, v[40:41]
	v_lshlrev_b64 v[42:43], 12, v[42:43]
	v_or_b32_e32 v44, 46, v2
	v_mov_b32_e32 v45, v3
	v_lshl_add_u64 v[30:31], v[28:29], 0, v[30:31]
	v_lshl_add_u64 v[32:33], v[28:29], 0, v[32:33]
	v_lshl_add_u64 v[34:35], v[28:29], 0, v[34:35]
	v_lshl_add_u64 v[36:37], v[28:29], 0, v[36:37]
	v_lshl_add_u64 v[38:39], v[28:29], 0, v[38:39]
	v_lshl_add_u64 v[40:41], v[28:29], 0, v[40:41]
	v_lshl_add_u64 v[42:43], v[28:29], 0, v[42:43]
	v_lshlrev_b64 v[44:45], 12, v[44:45]
	v_lshl_add_u64 v[44:45], v[28:29], 0, v[44:45]
	global_load_dword v82, v[30:31], off nt
	global_load_dword v83, v[32:33], off nt
	global_load_dword v84, v[34:35], off nt
	global_load_dword v85, v[36:37], off nt
	global_load_dword v86, v[38:39], off nt
	global_load_dword v87, v[40:41], off nt
	global_load_dword v88, v[42:43], off nt
	global_load_dword v89, v[44:45], off nt
	v_or_b32_e32 v30, 48, v2
	v_mov_b32_e32 v31, v3
	v_or_b32_e32 v32, 50, v2
	v_mov_b32_e32 v33, v3
	v_or_b32_e32 v34, 52, v2
	v_mov_b32_e32 v35, v3
	v_or_b32_e32 v36, 54, v2
	v_mov_b32_e32 v37, v3
	v_or_b32_e32 v38, 56, v2
	v_mov_b32_e32 v39, v3
	v_or_b32_e32 v40, 58, v2
	v_mov_b32_e32 v41, v3
	v_or_b32_e32 v42, 60, v2
	v_mov_b32_e32 v43, v3
	v_or_b32_e32 v2, 62, v2
	v_lshlrev_b64 v[30:31], 12, v[30:31]
	v_lshlrev_b64 v[32:33], 12, v[32:33]
	v_lshlrev_b64 v[34:35], 12, v[34:35]
	v_lshlrev_b64 v[36:37], 12, v[36:37]
	v_lshlrev_b64 v[38:39], 12, v[38:39]
	v_lshlrev_b64 v[40:41], 12, v[40:41]
	v_lshlrev_b64 v[42:43], 12, v[42:43]
	v_lshlrev_b64 v[44:45], 12, v[2:3]
	v_lshl_add_u64 v[30:31], v[28:29], 0, v[30:31]
	v_lshl_add_u64 v[32:33], v[28:29], 0, v[32:33]
	v_lshl_add_u64 v[34:35], v[28:29], 0, v[34:35]
	v_lshl_add_u64 v[36:37], v[28:29], 0, v[36:37]
	v_lshl_add_u64 v[38:39], v[28:29], 0, v[38:39]
	v_lshl_add_u64 v[40:41], v[28:29], 0, v[40:41]
	v_lshl_add_u64 v[42:43], v[28:29], 0, v[42:43]
	v_lshl_add_u64 v[28:29], v[28:29], 0, v[44:45]
	global_load_dword v2, v[30:31], off nt
	s_nop 0
	global_load_dword v30, v[32:33], off nt
	global_load_dword v31, v[34:35], off nt
	s_nop 0
	global_load_dword v32, v[36:37], off nt
	global_load_dword v33, v[38:39], off nt
	global_load_dword v34, v[40:41], off nt
	global_load_dword v35, v[42:43], off nt
	s_nop 0
	global_load_dword v28, v[28:29], off nt
	s_waitcnt vmcnt(30)
; #define GAS __attribute__((address_space(1)))
; #define LAS __attribute__((address_space(3)))
; #define LDS_WAIT() asm volatile("s_waitcnt lgkmcnt(0)" ::: "memory")
; __device__ __forceinline__ unsigned pk2(float lo, float hi) { return f2bf(lo) | (f2bf(hi) << 16); }
;     ...
;     for (int i = 0; i < 32; ++i) { const int kk = 2 * i + (lane >> 5); wv[i] = __builtin_nontemporal_load(W + (size_t)(k0 + kk) * ldw + src_c0 + (lane & 31)); }
; #pragma unroll
;     for (int i = 0; i < 32; ++i) { const int kk = 2 * i + (lane >> 5); float w = wv[i] * cscale; if (kgain) w *= kgain[k0 + kk]; scr[kk * 33 + (lane & 31)] = w; }
;     LDS_WAIT(); asm volatile("" ::: "memory");
;     const int c = lane & 7;
; #pragma unroll
;     for (int j = 0; j < 4; ++j) { const int n = (lane >> 3) + 8 * j; const LAS float* s = scr + (8 * c) * 33 + n;
;         v4u o; o.x = pk2(s[0 * 33], s[1 * 33]); o.y = pk2(s[2 * 33], s[3 * 33]); o.z = pk2(s[4 * 33], s[5 * 33]); o.w = pk2(s[6 * 33], s[7 * 33]);
;         *(GAS v4u*)(WT + (size_t)(dst_r0 + n) * K + k0 + 8 * c) = o; }
;     LDS_WAIT(); asm volatile("" ::: "memory");
	ds_write2_b32 v49, v46, v47 offset1:66
	s_waitcnt vmcnt(28)
	ds_write2_b32 v49, v68, v69 offset0:132 offset1:198
	s_waitcnt vmcnt(26)
	ds_write2_b32 v58, v70, v71 offset0:8 offset1:74
	s_waitcnt vmcnt(24)
	ds_write2_b32 v58, v72, v73 offset0:140 offset1:206
	s_waitcnt vmcnt(22)
	ds_write2_b32 v59, v74, v75 offset0:16 offset1:82
	s_waitcnt vmcnt(20)
	ds_write2_b32 v59, v76, v77 offset0:148 offset1:214
	s_waitcnt vmcnt(18)
	ds_write2_b32 v60, v78, v79 offset0:24 offset1:90
	s_waitcnt vmcnt(16)
	ds_write2_b32 v60, v80, v81 offset0:156 offset1:222
	s_waitcnt vmcnt(14)
	ds_write2_b32 v61, v82, v83 offset0:32 offset1:98
	s_waitcnt vmcnt(12)
	ds_write2_b32 v61, v84, v85 offset0:164 offset1:230
	s_waitcnt vmcnt(10)
	ds_write2_b32 v62, v86, v87 offset0:40 offset1:106
	s_waitcnt vmcnt(8)
	ds_write2_b32 v62, v88, v89 offset0:172 offset1:238
	s_waitcnt vmcnt(6)
	ds_write2_b32 v63, v2, v30 offset0:48 offset1:114
	s_waitcnt vmcnt(4)
	ds_write2_b32 v63, v31, v32 offset0:180 offset1:246
	s_waitcnt vmcnt(2)
	ds_write2_b32 v64, v33, v34 offset0:56 offset1:122
	s_waitcnt vmcnt(0)
	ds_write2_b32 v64, v35, v28 offset0:188 offset1:254
	s_waitcnt lgkmcnt(0)
	ds_read2_b32 v[32:33], v51 offset1:8
	ds_read2_b32 v[36:37], v51 offset0:33 offset1:41
	ds_read2_b32 v[38:39], v51 offset0:66 offset1:74
	ds_read2_b32 v[40:41], v51 offset0:99 offset1:107
	ds_read2_b32 v[42:43], v51 offset0:132 offset1:140
	s_waitcnt lgkmcnt(4)
	v_bfe_u32 v2, v32, 16, 1
	v_add3_u32 v2, v32, v2, s19
	s_waitcnt lgkmcnt(3)
	v_bfe_u32 v28, v36, 16, 1
	v_lshrrev_b32_e32 v2, 16, v2
	v_add3_u32 v28, v36, v28, s19
	ds_read2_b32 v[44:45], v51 offset0:165 offset1:173
	v_and_or_b32 v28, v28, s20, v2
	s_waitcnt lgkmcnt(3)
	v_bfe_u32 v2, v38, 16, 1
	v_add3_u32 v2, v38, v2, s19
	s_waitcnt lgkmcnt(2)
	v_bfe_u32 v29, v40, 16, 1
	ds_read2_b32 v[46:47], v51 offset0:198 offset1:206
	v_lshrrev_b32_e32 v2, 16, v2
	v_add3_u32 v29, v40, v29, s19
	ds_read2_b32 v[68:69], v51 offset0:231 offset1:239
	v_and_or_b32 v29, v29, s20, v2
	s_waitcnt lgkmcnt(3)
	v_bfe_u32 v2, v42, 16, 1
	v_add3_u32 v2, v42, v2, s19
	s_waitcnt lgkmcnt(2)
	v_bfe_u32 v30, v44, 16, 1
	v_lshrrev_b32_e32 v2, 16, v2
	v_add3_u32 v30, v44, v30, s19
	v_and_or_b32 v30, v30, s20, v2
	s_waitcnt lgkmcnt(1)
	v_bfe_u32 v2, v46, 16, 1
	v_add3_u32 v2, v46, v2, s19
	s_waitcnt lgkmcnt(0)
	v_bfe_u32 v31, v68, 16, 1
	v_lshrrev_b32_e32 v2, 16, v2
	v_add3_u32 v31, v68, v31, s19
	s_lshl_b32 s8, s3, 1
	v_and_or_b32 v31, v31, s20, v2
	v_or_b32_e32 v2, s2, v50
	v_lshl_add_u64 v[34:35], v[26:27], 0, s[8:9]
	v_lshlrev_b32_e32 v2, 10, v2
	v_lshl_add_u64 v[70:71], v[34:35], 0, v[2:3]
	v_bfe_u32 v2, v33, 16, 1
	global_store_dwordx4 v[70:71], v[28:31], off sc1
	v_add3_u32 v2, v33, v2, s19
	v_lshrrev_b32_e32 v2, 16, v2
	v_bfe_u32 v28, v37, 16, 1
	v_add3_u32 v28, v37, v28, s19
	v_and_or_b32 v28, v28, s20, v2
	v_bfe_u32 v2, v39, 16, 1
	v_add3_u32 v2, v39, v2, s19
	v_bfe_u32 v29, v41, 16, 1
	v_lshrrev_b32_e32 v2, 16, v2
	v_add3_u32 v29, v41, v29, s19
	v_and_or_b32 v29, v29, s20, v2
	v_bfe_u32 v2, v43, 16, 1
	v_add3_u32 v2, v43, v2, s19
	v_bfe_u32 v30, v45, 16, 1
	v_lshrrev_b32_e32 v2, 16, v2
	v_add3_u32 v30, v45, v30, s19
	v_and_or_b32 v30, v30, s20, v2
	v_bfe_u32 v2, v47, 16, 1
	v_add3_u32 v2, v47, v2, s19
	v_bfe_u32 v31, v69, 16, 1
	v_lshrrev_b32_e32 v2, 16, v2
	v_add3_u32 v31, v69, v31, s19
	v_and_or_b32 v31, v31, s20, v2
	v_or_b32_e32 v2, s2, v52
	v_lshlrev_b32_e32 v2, 10, v2
	ds_read2_b32 v[32:33], v51 offset0:16 offset1:24
	v_lshl_add_u64 v[36:37], v[34:35], 0, v[2:3]
	global_store_dwordx4 v[36:37], v[28:31], off sc1
	ds_read2_b32 v[36:37], v51 offset0:49 offset1:57
	ds_read2_b32 v[38:39], v51 offset0:82 offset1:90
	ds_read2_b32 v[40:41], v51 offset0:115 offset1:123
	s_waitcnt lgkmcnt(3)
	v_bfe_u32 v2, v32, 16, 1
	v_add3_u32 v2, v32, v2, s19
	s_waitcnt lgkmcnt(2)
	v_bfe_u32 v28, v36, 16, 1
	ds_read2_b32 v[42:43], v51 offset0:148 offset1:156
	v_lshrrev_b32_e32 v2, 16, v2
	v_add3_u32 v28, v36, v28, s19
	ds_read2_b32 v[44:45], v51 offset0:181 offset1:189
	v_and_or_b32 v28, v28, s20, v2
	s_waitcnt lgkmcnt(3)
	v_bfe_u32 v2, v38, 16, 1
	v_add3_u32 v2, v38, v2, s19
	s_waitcnt lgkmcnt(2)
	v_bfe_u32 v29, v40, 16, 1
	ds_read2_b32 v[46:47], v51 offset0:214 offset1:222
	v_lshrrev_b32_e32 v2, 16, v2
	v_add3_u32 v29, v40, v29, s19
	ds_read2_b32 v[68:69], v51 offset0:247 offset1:255
	v_and_or_b32 v29, v29, s20, v2
	s_waitcnt lgkmcnt(3)
	v_bfe_u32 v2, v42, 16, 1
	v_add3_u32 v2, v42, v2, s19
	s_waitcnt lgkmcnt(2)
	v_bfe_u32 v30, v44, 16, 1
	v_lshrrev_b32_e32 v2, 16, v2
	v_add3_u32 v30, v44, v30, s19
	v_and_or_b32 v30, v30, s20, v2
	s_waitcnt lgkmcnt(1)
	v_bfe_u32 v2, v46, 16, 1
	v_add3_u32 v2, v46, v2, s19
	s_waitcnt lgkmcnt(0)
	v_bfe_u32 v31, v68, 16, 1
	v_lshrrev_b32_e32 v2, 16, v2
	v_add3_u32 v31, v68, v31, s19
	v_and_or_b32 v31, v31, s20, v2
	v_or_b32_e32 v2, s2, v53
	v_lshlrev_b32_e32 v2, 10, v2
	v_lshl_add_u64 v[70:71], v[34:35], 0, v[2:3]
	v_bfe_u32 v2, v33, 16, 1
	global_store_dwordx4 v[70:71], v[28:31], off sc1
	v_add3_u32 v2, v33, v2, s19
	v_lshrrev_b32_e32 v2, 16, v2
	v_bfe_u32 v28, v37, 16, 1
	v_add3_u32 v28, v37, v28, s19
	v_and_or_b32 v28, v28, s20, v2
	v_bfe_u32 v2, v39, 16, 1
	v_add3_u32 v2, v39, v2, s19
	v_bfe_u32 v29, v41, 16, 1
	v_lshrrev_b32_e32 v2, 16, v2
	v_add3_u32 v29, v41, v29, s19
	v_and_or_b32 v29, v29, s20, v2
	v_bfe_u32 v2, v43, 16, 1
	v_add3_u32 v2, v43, v2, s19
	v_bfe_u32 v30, v45, 16, 1
	v_lshrrev_b32_e32 v2, 16, v2
	v_add3_u32 v30, v45, v30, s19
	v_and_or_b32 v30, v30, s20, v2
	v_bfe_u32 v2, v47, 16, 1
	v_add3_u32 v2, v47, v2, s19
	v_bfe_u32 v31, v69, 16, 1
	v_lshrrev_b32_e32 v2, 16, v2
	v_add3_u32 v31, v69, v31, s19
	v_and_or_b32 v31, v31, s20, v2
	v_or_b32_e32 v2, s2, v54
	v_lshlrev_b32_e32 v2, 10, v2
	v_lshl_add_u64 v[32:33], v[34:35], 0, v[2:3]
	global_store_dwordx4 v[32:33], v[28:31], off sc1
	s_waitcnt lgkmcnt(0)
	s_branch .LBB0_268

; __device__ __forceinline__ unsigned xb_ld(unsigned* p)              { return __hip_atomic_load(p, __ATOMIC_RELAXED, __HIP_MEMORY_SCOPE_AGENT); }
; __device__ __forceinline__ unsigned xb_add(unsigned* p, unsigned v) { return __hip_atomic_fetch_add(p, v, __ATOMIC_RELAXED, __HIP_MEMORY_SCOPE_AGENT); }
; #define XB_SPIN(cond, bar) do { unsigned _sp = 0; while (cond) { __builtin_amdgcn_s_sleep(1); \
;     if ((++_sp & 255u) == 0u) { if (xb_ld(&(bar)[XB_TMO])) break; if (_sp > XB_SPIN_CAP) { atomicAdd(&(bar)[XB_TMO], 1u); break; } } } } while (0)
; __device__ __forceinline__ void xcd_barrier(const XcdBarrier& b) {
;     asm volatile("s_waitcnt vmcnt(0)" ::: "memory");
;     __syncthreads();
;     if (threadIdx.x == 0) {
;         unsigned* bar = b.bar;
;         __builtin_amdgcn_s_waitcnt(0);
;         unsigned nloc = b.st[0], nx = b.st[1];
;         if (nloc == 0u) { xcd_barrier_complete(bar, b.x, nloc, nx); b.st[0] = nloc; b.st[1] = nx; }
;         const unsigned old = xb_add(&bar[XB_XSUB(b.x)], 1u);
;         const unsigned gen = old / nloc;
;         if (old + 1u == (gen + 1u) * nloc) {
;             __builtin_amdgcn_fence(__ATOMIC_RELEASE, "agent");
;             asm volatile("s_waitcnt vmcnt(0)" ::: "memory");
;             const unsigned og = xb_add(&bar[XB_TOP], 1u);
;             const unsigned tg = og / nx;
;             if (og + 1u == (tg + 1u) * nx) xb_add(&bar[XB_TOPGEN], 1u);
;             else XB_SPIN(xb_ld(&bar[XB_TOPGEN]) == tg, bar);
;             __builtin_amdgcn_fence(__ATOMIC_ACQUIRE, "agent");
;             xb_add(&bar[XB_XGEN(b.x)], 1u);
;             asm volatile("s_waitcnt vmcnt(0)" ::: "memory");
;         } else {
;             XB_SPIN(xb_ld(&bar[XB_XGEN(b.x)]) == gen, bar);
;             __builtin_amdgcn_fence(__ATOMIC_ACQUIRE, "agent");
;             asm volatile("s_waitcnt vmcnt(0)" ::: "memory");
;         }
;     }
;     __syncthreads();
; }
.Lgrpbar3_same:
	buffer_inv sc1
	global_atomic_add v1, v2, s[2:3]
	s_add_u32 s6, s62, 0xd000
	s_addc_u32 s7, s63, 0
	global_atomic_add v1, v2, s[6:7]

; __device__ __forceinline__ unsigned xb_ld(unsigned* p)              { return __hip_atomic_load(p, __ATOMIC_RELAXED, __HIP_MEMORY_SCOPE_AGENT); }
; __device__ __forceinline__ unsigned xb_add(unsigned* p, unsigned v) { return __hip_atomic_fetch_add(p, v, __ATOMIC_RELAXED, __HIP_MEMORY_SCOPE_AGENT); }
; #define XB_SPIN(cond, bar) do { unsigned _sp = 0; while (cond) { __builtin_amdgcn_s_sleep(1); \
;     if ((++_sp & 255u) == 0u) { if (xb_ld(&(bar)[XB_TMO])) break; if (_sp > XB_SPIN_CAP) { atomicAdd(&(bar)[XB_TMO], 1u); break; } } } } while (0)
; #define GRID_BAR() do { if (N_LAUNCHES == 1) xcd_barrier(bar); } while (0)
; #define BOTH(k) (IN(k) && IN((k) + 1))
; __device__ __forceinline__ void xcd_barrier(const XcdBarrier& b) {
;     asm volatile("s_waitcnt vmcnt(0)" ::: "memory");
;     __syncthreads();
;     if (threadIdx.x == 0) {
;         unsigned* bar = b.bar;
;         __builtin_amdgcn_s_waitcnt(0);
;         unsigned nloc = b.st[0], nx = b.st[1];
;         if (nloc == 0u) { xcd_barrier_complete(bar, b.x, nloc, nx); b.st[0] = nloc; b.st[1] = nx; }
;         const unsigned old = xb_add(&bar[XB_XSUB(b.x)], 1u);
;         const unsigned gen = old / nloc;
;         if (old + 1u == (gen + 1u) * nloc) {
;             __builtin_amdgcn_fence(__ATOMIC_RELEASE, "agent");
;             asm volatile("s_waitcnt vmcnt(0)" ::: "memory");
;             const unsigned og = xb_add(&bar[XB_TOP], 1u);
;             const unsigned tg = og / nx;
;             if (og + 1u == (tg + 1u) * nx) xb_add(&bar[XB_TOPGEN], 1u);
;             else XB_SPIN(xb_ld(&bar[XB_TOPGEN]) == tg, bar);
;             __builtin_amdgcn_fence(__ATOMIC_ACQUIRE, "agent");
;             xb_add(&bar[XB_XGEN(b.x)], 1u);
;             asm volatile("s_waitcnt vmcnt(0)" ::: "memory");
;         } else {
;             XB_SPIN(xb_ld(&bar[XB_XGEN(b.x)]) == gen, bar);
;             __builtin_amdgcn_fence(__ATOMIC_ACQUIRE, "agent");
;             asm volatile("s_waitcnt vmcnt(0)" ::: "memory");
;         }
; __global__ void __launch_bounds__(NTHREADS, 2) skel_fwd(Args args) {
;     ...
;         if (BOTH(3)) GRID_BAR();
.LBB0_507:
	v_readlane_b32 s18, v247, 47
	v_readlane_b32 s19, v247, 48
	s_cmp_gt_i32 s19, 4
	s_cbranch_scc0 .LBB0_561
	s_waitcnt vmcnt(0)
	s_waitcnt vmcnt(0) lgkmcnt(0)
	s_barrier
	s_mov_b64 s[0:1], exec
	v_readlane_b32 s2, v247, 37
	v_readlane_b32 s3, v247, 38
	s_and_b64 s[2:3], s[0:1], s[2:3]
	s_mov_b64 exec, s[2:3]
	s_cbranch_execz .LBB0_560
	v_readlane_b32 s5, v247, 36
	s_and_b32 s2, s90, 7
	s_lshl_b32 s2, s2, 7
	s_add_u32 s2, s62, s2
	s_addc_u32 s3, s63, 0
	s_lshr_b32 s6, s5, 2
	s_and_b32 s6, s6, 1
	s_lshl_b32 s6, s6, 6
	s_add_u32 s6, s2, s6
	s_addc_u32 s7, s3, 0
	s_add_u32 s6, s6, 0xa800
	s_addc_u32 s7, s7, 0
	s_add_u32 s2, s2, 0xf000
	s_addc_u32 s3, s3, 0
	s_and_b32 s5, s5, 3
	s_lshl_b32 s5, s5, 3
	s_lshl_b32 s5, 32, s5
	v_mov_b32_e32 v1, 0
	global_load_dword v3, v1, s[6:7] sc1
	v_mov_b32_e32 v2, 1
	s_mov_b32 s4, 0
	s_waitcnt vmcnt(0) lgkmcnt(0)
	v_cmp_eq_u32_e32 vcc, s5, v3
	s_mov_b32 s5, 1
	s_cbranch_vccnz .Lgrpbar4_same
	s_mov_b32 s5, 0
	buffer_wbl2 sc1
	s_waitcnt vmcnt(0)
.Lgrpbar4_same:
	buffer_inv sc1
	global_atomic_add v1, v2, s[2:3]
	s_add_u32 s6, s62, 0xd000
	s_addc_u32 s7, s63, 0
.Lgrpbar4_spin:
	global_load_dword v3, v1, s[2:3] sc1
	s_waitcnt vmcnt(0)
	v_cmp_lt_u32_e32 vcc, 31, v3
	s_cbranch_vccnz .Lgrpbar4_done
	s_sleep 1
	s_add_i32 s4, s4, 1
	s_cmp_lt_u32 s4, 0x200000
	s_cbranch_scc1 .Lgrpbar4_spin
.Lgrpbar4_done:
.Lgrpbar4_wspin:
	global_load_dword v3, v1, s[6:7] sc1
	s_waitcnt vmcnt(0)
	v_cmp_lt_u32_e32 vcc, 0xff, v3
	s_cbranch_vccnz .Lgrpbar4_wdone
	s_sleep 1
	s_add_i32 s4, s4, 1
	s_cmp_lt_u32 s4, 0x200000
	s_cbranch_scc1 .Lgrpbar4_wspin
.Lgrpbar4_wdone:
	s_and_b32 s6, s90, 7
	s_cmp_lg_u32 s6, 0
	s_cbranch_scc1 .Lgrpbar4_mdone
	s_bfe_u32 s6, s90, 0x10007
	s_lshl_b32 s6, s6, 2
	s_bfe_u32 s7, s90, 0x20003
	s_or_b32 s6, s6, s7
	s_lshl_b32 s6, s6, 7
	s_add_u32 s6, s62, s6
	s_addc_u32 s7, s63, 0
	s_add_u32 s6, s6, 0xf000
	s_addc_u32 s7, s7, 0
.Lgrpbar4_mspin:
	global_load_dword v3, v1, s[6:7] sc1
	s_waitcnt vmcnt(0)
	v_cmp_lt_u32_e32 vcc, 31, v3
	s_cbranch_vccnz .Lgrpbar4_mdone
	s_sleep 1
	s_add_i32 s4, s4, 1
	s_cmp_lt_u32 s4, 0x200000
	s_cbranch_scc1 .Lgrpbar4_mspin

; __device__ __forceinline__ unsigned xb_ld(unsigned* p)              { return __hip_atomic_load(p, __ATOMIC_RELAXED, __HIP_MEMORY_SCOPE_AGENT); }
; #define XB_SPIN(cond, bar) do { unsigned _sp = 0; while (cond) { __builtin_amdgcn_s_sleep(1); \
;     if ((++_sp & 255u) == 0u) { if (xb_ld(&(bar)[XB_TMO])) break; if (_sp > XB_SPIN_CAP) { atomicAdd(&(bar)[XB_TMO], 1u); break; } } } } while (0)
; __device__ __forceinline__ void xcd_barrier(const XcdBarrier& b) {
;     ...
;         } else {
;             XB_SPIN(xb_ld(&bar[XB_XGEN(b.x)]) == gen, bar);
;             __builtin_amdgcn_fence(__ATOMIC_ACQUIRE, "agent");
;             asm volatile("s_waitcnt vmcnt(0)" ::: "memory");
;         }
;     }
;     __syncthreads();
; }
; __global__ void __launch_bounds__(NTHREADS, 2) skel_fwd(Args args) {
;     ...
;     if (IN(4)) {
;     ...
;         { pg8::SchedP3m S{F.G, (int)blockIdx.x, (const char*)F.SBQ, (const char*)F.Wbr_t};
;           pg8::EpiMergedR E{F.G0, F.G2, F.MRG};
;           pg8::gemm_phase<pg8::EpiMergedR, pg8::SchedP3m, true, true, 3>(F.lds, DH, S, E); }
.Lgrpbar4_noinv:
.LBB0_560:
	s_or_b64 exec, exec, s[0:1]
	s_waitcnt lgkmcnt(0)
	s_barrier
.LBB0_561:
	s_cmp_lt_i32 s18, 5
	s_cselect_b64 s[0:1], -1, 0
	s_cmp_gt_i32 s19, 4
	s_cselect_b64 s[2:3], -1, 0
	s_and_b64 s[0:1], s[0:1], s[2:3]
	v_readlane_b32 s58, v247, 41
	v_readlane_b32 s50, v247, 43
	s_andn2_b64 vcc, exec, s[0:1]
	v_readlane_b32 s59, v247, 42
	v_readlane_b32 s51, v247, 44
	s_cbranch_vccnz .LBB0_782
	s_cmpk_lt_i32 s90, 0x100
	v_readlane_b32 s48, v247, 39
	s_cselect_b64 s[0:1], -1, 0
	s_cmpk_gt_i32 s90, 0xff
	v_readfirstlane_b32 s7, v0
	v_readlane_b32 s49, v247, 40
	s_cbranch_scc0 .LBB0_565
	s_andn2_b64 vcc, exec, s[0:1]
	s_cbranch_vccz .LBB0_570
